# hand-written attention q/k prep (RMSNorm+rotary): 4 elements per lane, DPP reductions, all loads in flight; both layers
# speedup vs baseline: 1.0361x; 1.0361x over previous
.LBB0_1118:
	s_barrier
	v_lshrrev_b32_e32 v0, 6, v194
	s_lshl_b32 s23, s64, 3
	v_readfirstlane_b32 s22, v0
	s_lshl_b32 s24, s2, 3
	s_add_i32 s22, s22, s24
	s_cmp_lt_u32 s22, 0x2000
	s_cbranch_scc0 .Lprep_done_L0
	s_add_u32 s0, s66, 0x8000
	s_addc_u32 s1, s67, 0
	s_add_u32 s6, s66, 0x5801000
	s_addc_u32 s7, s67, 0
	v_and_b32_e32 v0, 63, v194
	v_mov_b32_e32 v11, 0
	v_and_b32_e32 v1, 15, v0
	v_lshlrev_b32_e32 v2, 3, v0
	v_add_u32_e32 v3, 0x1800, v2
	v_cmp_lt_u32_e32 vcc, 31, v0
	v_mov_b32_e32 v20, 0x1700
	s_nop 1
	v_cndmask_b32_e32 v20, 0, v20, vcc
	v_add_u32_e32 v4, v2, v20
	v_and_b32_e32 v21, 4, v1
	v_cmp_ne_u32_e32 vcc, 0, v21
	v_mov_b32_e32 v22, 1.0
	v_mov_b32_e32 v5, -1.0
	v_cndmask_b32_e32 v5, v5, v22, vcc
	v_mov_b32_e32 v6, 0x358637bd
	v_cmp_gt_u32_e32 vcc, 8, v1
	s_nop 1
	v_cndmask_b32_e64 v7, 0, 1, vcc
	v_mov_b32_e32 v22, 0x80
	v_cndmask_b32_e32 v8, v22, v11, vcc
	v_cmp_lt_u32_e32 vcc, 31, v0
	s_nop 1
	v_cndmask_b32_e32 v9, 0, v8, vcc
	v_and_b32_e32 v10, 3, v1
	v_lshlrev_b32_e32 v10, 5, v10
	global_load_dwordx4 v[24:27], v11, s[66:67] offset:152
	v_lshlrev_b32_e32 v20, 4, v1
	v_mov_b32_e32 v21, 0
	s_waitcnt vmcnt(0)
	v_lshl_add_u64 v[24:25], v[24:25], 0, v[20:21]
	v_lshl_add_u64 v[26:27], v[26:27], 0, v[20:21]
	global_load_dwordx4 v[12:15], v[24:25], off
	global_load_dwordx4 v[16:19], v[26:27], off
.Lprep_loop_L0:
	s_mov_b32 s34, s22
	s_mul_i32 s25, s34, 0x3000
	s_add_u32 s14, s6, s25
	s_addc_u32 s15, s7, 0
	s_lshl_b32 s25, s34, 1
	s_and_b32 s25, s25, 0xfff
	s_lshr_b32 s30, s25, 6
	s_and_b32 s31, s25, 63
	s_sub_i32 s30, s30, s31
	s_lshl_b32 s30, s30, 7
	s_lshl_b32 s31, s31, 7
	v_add_u32_e32 v236, s31, v10
	v_mad_i32_i24 v236, v7, s30, v236
	v_add_u32_e32 v237, v236, v8
	v_add_u32_e32 v238, v236, v9
	global_load_dwordx4 v[68:71], v236, s[0:1]
	global_load_dwordx4 v[72:75], v236, s[0:1] offset:16
	global_load_dwordx4 v[76:79], v237, s[0:1]
	global_load_dwordx4 v[80:83], v237, s[0:1] offset:16
	global_load_dwordx4 v[84:87], v238, s[0:1]
	global_load_dwordx4 v[88:91], v238, s[0:1] offset:16
	global_load_dwordx2 v[28:29], v2, s[14:15]
	global_load_dwordx2 v[30:31], v2, s[14:15] offset:512
	global_load_dwordx2 v[32:33], v3, s[14:15]
	global_load_dwordx2 v[34:35], v3, s[14:15] offset:512
	global_load_dwordx2 v[36:37], v4, s[14:15] offset:1024
	s_mul_i32 s24, s23, 1
	s_add_i32 s24, s24, s22
	s_cmp_lt_u32 s24, 0x2000
	s_cselect_b32 s34, s24, s22
	s_mul_i32 s25, s34, 0x3000
	s_add_u32 s16, s6, s25
	s_addc_u32 s17, s7, 0
	s_lshl_b32 s25, s34, 1
	s_and_b32 s25, s25, 0xfff
	s_lshr_b32 s30, s25, 6
	s_and_b32 s31, s25, 63
	s_sub_i32 s30, s30, s31
	s_lshl_b32 s30, s30, 7
	s_lshl_b32 s31, s31, 7
	v_add_u32_e32 v236, s31, v10
	v_mad_i32_i24 v236, v7, s30, v236
	v_add_u32_e32 v237, v236, v8
	v_add_u32_e32 v238, v236, v9
	global_load_dwordx4 v[92:95], v236, s[0:1]
	global_load_dwordx4 v[96:99], v236, s[0:1] offset:16
	global_load_dwordx4 v[100:103], v237, s[0:1]
	global_load_dwordx4 v[104:107], v237, s[0:1] offset:16
	global_load_dwordx4 v[108:111], v238, s[0:1]
	global_load_dwordx4 v[112:115], v238, s[0:1] offset:16
	global_load_dwordx2 v[38:39], v2, s[16:17]
	global_load_dwordx2 v[40:41], v2, s[16:17] offset:512
	global_load_dwordx2 v[42:43], v3, s[16:17]
	global_load_dwordx2 v[44:45], v3, s[16:17] offset:512
	global_load_dwordx2 v[46:47], v4, s[16:17] offset:1024
	s_mul_i32 s24, s23, 2
	s_add_i32 s24, s24, s22
	s_cmp_lt_u32 s24, 0x2000
	s_cselect_b32 s34, s24, s22
	s_mul_i32 s25, s34, 0x3000
	s_add_u32 s18, s6, s25
	s_addc_u32 s19, s7, 0
	s_lshl_b32 s25, s34, 1
	s_and_b32 s25, s25, 0xfff
	s_lshr_b32 s30, s25, 6
	s_and_b32 s31, s25, 63
	s_sub_i32 s30, s30, s31
	s_lshl_b32 s30, s30, 7
	s_lshl_b32 s31, s31, 7
	v_add_u32_e32 v236, s31, v10
	v_mad_i32_i24 v236, v7, s30, v236
	v_add_u32_e32 v237, v236, v8
	v_add_u32_e32 v238, v236, v9
	global_load_dwordx4 v[116:119], v236, s[0:1]
	global_load_dwordx4 v[120:123], v236, s[0:1] offset:16
	global_load_dwordx4 v[124:127], v237, s[0:1]
	global_load_dwordx4 v[128:131], v237, s[0:1] offset:16
	global_load_dwordx4 v[132:135], v238, s[0:1]
	global_load_dwordx4 v[136:139], v238, s[0:1] offset:16
	global_load_dwordx2 v[48:49], v2, s[18:19]
	global_load_dwordx2 v[50:51], v2, s[18:19] offset:512
	global_load_dwordx2 v[52:53], v3, s[18:19]
	global_load_dwordx2 v[54:55], v3, s[18:19] offset:512
	global_load_dwordx2 v[56:57], v4, s[18:19] offset:1024
	s_mul_i32 s24, s23, 3
	s_add_i32 s24, s24, s22
	s_cmp_lt_u32 s24, 0x2000
	s_cselect_b32 s34, s24, s22
	s_mul_i32 s25, s34, 0x3000
	s_add_u32 s20, s6, s25
	s_addc_u32 s21, s7, 0
	s_lshl_b32 s25, s34, 1
	s_and_b32 s25, s25, 0xfff
	s_lshr_b32 s30, s25, 6
	s_and_b32 s31, s25, 63
	s_sub_i32 s30, s30, s31
	s_lshl_b32 s30, s30, 7
	s_lshl_b32 s31, s31, 7
	v_add_u32_e32 v236, s31, v10
	v_mad_i32_i24 v236, v7, s30, v236
	v_add_u32_e32 v237, v236, v8
	v_add_u32_e32 v238, v236, v9
	global_load_dwordx4 v[140:143], v236, s[0:1]
	global_load_dwordx4 v[144:147], v236, s[0:1] offset:16
	global_load_dwordx4 v[148:151], v237, s[0:1]
	global_load_dwordx4 v[152:155], v237, s[0:1] offset:16
	global_load_dwordx4 v[156:159], v238, s[0:1]
	global_load_dwordx4 v[160:163], v238, s[0:1] offset:16
	global_load_dwordx2 v[58:59], v2, s[20:21]
	global_load_dwordx2 v[60:61], v2, s[20:21] offset:512
	global_load_dwordx2 v[62:63], v3, s[20:21]
	global_load_dwordx2 v[64:65], v3, s[20:21] offset:512
	global_load_dwordx2 v[66:67], v4, s[20:21] offset:1024
	s_waitcnt vmcnt(33)
	v_mul_f32_e32 v69, v5, v69
	v_mul_f32_e32 v71, v5, v71
	v_mul_f32_e32 v73, v5, v73
	v_mul_f32_e32 v75, v5, v75
	v_mul_f32_e32 v77, v5, v77
	v_mul_f32_e32 v79, v5, v79
	v_mul_f32_e32 v81, v5, v81
	v_mul_f32_e32 v83, v5, v83
	v_mul_f32_e32 v85, v5, v85
	v_mul_f32_e32 v87, v5, v87
	v_mul_f32_e32 v89, v5, v89
	v_mul_f32_e32 v91, v5, v91
	v_lshlrev_b32_e32 v164, 16, v28
	v_and_b32_e32 v165, 0xffff0000, v28
	v_lshlrev_b32_e32 v166, 16, v29
	v_and_b32_e32 v167, 0xffff0000, v29
	v_lshlrev_b32_e32 v168, 16, v30
	v_and_b32_e32 v169, 0xffff0000, v30
	v_lshlrev_b32_e32 v170, 16, v31
	v_and_b32_e32 v171, 0xffff0000, v31
	v_lshlrev_b32_e32 v172, 16, v32
	v_and_b32_e32 v173, 0xffff0000, v32
	v_lshlrev_b32_e32 v174, 16, v33
	v_and_b32_e32 v175, 0xffff0000, v33
	v_lshlrev_b32_e32 v176, 16, v34
	v_and_b32_e32 v177, 0xffff0000, v34
	v_lshlrev_b32_e32 v178, 16, v35
	v_and_b32_e32 v179, 0xffff0000, v35
	v_lshlrev_b32_e32 v180, 16, v36
	v_and_b32_e32 v181, 0xffff0000, v36
	v_lshlrev_b32_e32 v182, 16, v37
	v_and_b32_e32 v183, 0xffff0000, v37
	v_mul_f32_e32 v184, v164, v164
	v_fmac_f32_e32 v184, v165, v165
	v_fmac_f32_e32 v184, v166, v166
	v_fmac_f32_e32 v184, v167, v167
	v_mul_f32_e32 v185, v168, v168
	v_fmac_f32_e32 v185, v169, v169
	v_fmac_f32_e32 v185, v170, v170
	v_fmac_f32_e32 v185, v171, v171
	v_mul_f32_e32 v186, v172, v172
	v_fmac_f32_e32 v186, v173, v173
	v_fmac_f32_e32 v186, v174, v174
	v_fmac_f32_e32 v186, v175, v175
	v_mul_f32_e32 v187, v176, v176
	v_fmac_f32_e32 v187, v177, v177
	v_fmac_f32_e32 v187, v178, v178
	v_fmac_f32_e32 v187, v179, v179
	v_mul_f32_e32 v188, v180, v180
	v_fmac_f32_e32 v188, v181, v181
	v_fmac_f32_e32 v188, v182, v182
	v_fmac_f32_e32 v188, v183, v183
	v_add_f32_dpp v184, v184, v184 quad_perm:[1,0,3,2] row_mask:0xf bank_mask:0xf
	v_add_f32_dpp v185, v185, v185 quad_perm:[1,0,3,2] row_mask:0xf bank_mask:0xf
	v_add_f32_dpp v186, v186, v186 quad_perm:[1,0,3,2] row_mask:0xf bank_mask:0xf
	v_add_f32_dpp v187, v187, v187 quad_perm:[1,0,3,2] row_mask:0xf bank_mask:0xf
	v_add_f32_dpp v188, v188, v188 quad_perm:[1,0,3,2] row_mask:0xf bank_mask:0xf
	v_add_f32_dpp v184, v184, v184 quad_perm:[2,3,0,1] row_mask:0xf bank_mask:0xf
	v_add_f32_dpp v185, v185, v185 quad_perm:[2,3,0,1] row_mask:0xf bank_mask:0xf
	v_add_f32_dpp v186, v186, v186 quad_perm:[2,3,0,1] row_mask:0xf bank_mask:0xf
	v_add_f32_dpp v187, v187, v187 quad_perm:[2,3,0,1] row_mask:0xf bank_mask:0xf
	v_add_f32_dpp v188, v188, v188 quad_perm:[2,3,0,1] row_mask:0xf bank_mask:0xf
	v_add_f32_dpp v184, v184, v184 row_half_mirror row_mask:0xf bank_mask:0xf
	v_add_f32_dpp v185, v185, v185 row_half_mirror row_mask:0xf bank_mask:0xf
	v_add_f32_dpp v186, v186, v186 row_half_mirror row_mask:0xf bank_mask:0xf
	v_add_f32_dpp v187, v187, v187 row_half_mirror row_mask:0xf bank_mask:0xf
	v_add_f32_dpp v188, v188, v188 row_half_mirror row_mask:0xf bank_mask:0xf
	v_add_f32_dpp v184, v184, v184 row_mirror row_mask:0xf bank_mask:0xf
	v_add_f32_dpp v185, v185, v185 row_mirror row_mask:0xf bank_mask:0xf
	v_add_f32_dpp v186, v186, v186 row_mirror row_mask:0xf bank_mask:0xf
	v_add_f32_dpp v187, v187, v187 row_mirror row_mask:0xf bank_mask:0xf
	v_add_f32_dpp v188, v188, v188 row_mirror row_mask:0xf bank_mask:0xf
	v_fmamk_f32 v184, v184, 0x3c800000, v6
	v_fmamk_f32 v185, v185, 0x3c800000, v6
	v_fmamk_f32 v186, v186, 0x3c800000, v6
	v_fmamk_f32 v187, v187, 0x3c800000, v6
	v_fmamk_f32 v188, v188, 0x3c800000, v6
	v_rsq_f32_e32 v184, v184
	v_rsq_f32_e32 v185, v185
	v_rsq_f32_e32 v186, v186
	v_rsq_f32_e32 v187, v187
	v_rsq_f32_e32 v188, v188
	v_mul_f32_e32 v164, v184, v164
	v_mul_f32_e32 v165, v184, v165
	v_mul_f32_e32 v166, v184, v166
	v_mul_f32_e32 v167, v184, v167
	v_mul_f32_e32 v168, v185, v168
	v_mul_f32_e32 v169, v185, v169
	v_mul_f32_e32 v170, v185, v170
	v_mul_f32_e32 v171, v185, v171
	v_mul_f32_e32 v172, v186, v172
	v_mul_f32_e32 v173, v186, v173
	v_mul_f32_e32 v174, v186, v174
	v_mul_f32_e32 v175, v186, v175
	v_mul_f32_e32 v176, v187, v176
	v_mul_f32_e32 v177, v187, v177
	v_mul_f32_e32 v178, v187, v178
	v_mul_f32_e32 v179, v187, v179
	v_mul_f32_e32 v180, v188, v180
	v_mul_f32_e32 v181, v188, v181
	v_mul_f32_e32 v182, v188, v182
	v_mul_f32_e32 v183, v188, v183
	v_mul_f32_e32 v164, v12, v164
	v_mul_f32_e32 v165, v13, v165
	v_mul_f32_e32 v166, v14, v166
	v_mul_f32_e32 v167, v15, v167
	v_mul_f32_e32 v168, v12, v168
	v_mul_f32_e32 v169, v13, v169
	v_mul_f32_e32 v170, v14, v170
	v_mul_f32_e32 v171, v15, v171
	v_mul_f32_e32 v172, v12, v172
	v_mul_f32_e32 v173, v13, v173
	v_mul_f32_e32 v174, v14, v174
	v_mul_f32_e32 v175, v15, v175
	v_mul_f32_e32 v176, v12, v176
	v_mul_f32_e32 v177, v13, v177
	v_mul_f32_e32 v178, v14, v178
	v_mul_f32_e32 v179, v15, v179
	v_mul_f32_e32 v180, v16, v180
	v_mul_f32_e32 v181, v17, v181
	v_mul_f32_e32 v182, v18, v182
	v_mul_f32_e32 v183, v19, v183
	v_mov_b32_dpp v196, v164 row_half_mirror row_mask:0xf bank_mask:0xf
	v_mov_b32_dpp v197, v165 row_half_mirror row_mask:0xf bank_mask:0xf
	v_mov_b32_dpp v198, v166 row_half_mirror row_mask:0xf bank_mask:0xf
	v_mov_b32_dpp v199, v167 row_half_mirror row_mask:0xf bank_mask:0xf
	v_mov_b32_dpp v200, v168 row_half_mirror row_mask:0xf bank_mask:0xf
	v_mov_b32_dpp v201, v169 row_half_mirror row_mask:0xf bank_mask:0xf
	v_mov_b32_dpp v202, v170 row_half_mirror row_mask:0xf bank_mask:0xf
	v_mov_b32_dpp v203, v171 row_half_mirror row_mask:0xf bank_mask:0xf
	v_mov_b32_dpp v204, v172 row_half_mirror row_mask:0xf bank_mask:0xf
	v_mov_b32_dpp v205, v173 row_half_mirror row_mask:0xf bank_mask:0xf
	v_mov_b32_dpp v206, v174 row_half_mirror row_mask:0xf bank_mask:0xf
	v_mov_b32_dpp v207, v175 row_half_mirror row_mask:0xf bank_mask:0xf
	v_mov_b32_dpp v208, v176 row_half_mirror row_mask:0xf bank_mask:0xf
	v_mov_b32_dpp v209, v177 row_half_mirror row_mask:0xf bank_mask:0xf
	v_mov_b32_dpp v210, v178 row_half_mirror row_mask:0xf bank_mask:0xf
	v_mov_b32_dpp v211, v179 row_half_mirror row_mask:0xf bank_mask:0xf
	v_mov_b32_dpp v212, v180 row_half_mirror row_mask:0xf bank_mask:0xf
	v_mov_b32_dpp v213, v181 row_half_mirror row_mask:0xf bank_mask:0xf
	v_mov_b32_dpp v214, v182 row_half_mirror row_mask:0xf bank_mask:0xf
	v_mov_b32_dpp v215, v183 row_half_mirror row_mask:0xf bank_mask:0xf
	v_mov_b32_dpp v216, v196 quad_perm:[3,2,1,0] row_mask:0xf bank_mask:0xf
	v_mov_b32_dpp v217, v197 quad_perm:[3,2,1,0] row_mask:0xf bank_mask:0xf
	v_mov_b32_dpp v218, v198 quad_perm:[3,2,1,0] row_mask:0xf bank_mask:0xf
	v_mov_b32_dpp v219, v199 quad_perm:[3,2,1,0] row_mask:0xf bank_mask:0xf
	v_mov_b32_dpp v220, v200 quad_perm:[3,2,1,0] row_mask:0xf bank_mask:0xf
	v_mov_b32_dpp v221, v201 quad_perm:[3,2,1,0] row_mask:0xf bank_mask:0xf
	v_mov_b32_dpp v222, v202 quad_perm:[3,2,1,0] row_mask:0xf bank_mask:0xf
	v_mov_b32_dpp v223, v203 quad_perm:[3,2,1,0] row_mask:0xf bank_mask:0xf
	v_mov_b32_dpp v224, v204 quad_perm:[3,2,1,0] row_mask:0xf bank_mask:0xf
	v_mov_b32_dpp v225, v205 quad_perm:[3,2,1,0] row_mask:0xf bank_mask:0xf
	v_mov_b32_dpp v226, v206 quad_perm:[3,2,1,0] row_mask:0xf bank_mask:0xf
	v_mov_b32_dpp v227, v207 quad_perm:[3,2,1,0] row_mask:0xf bank_mask:0xf
	v_mov_b32_dpp v228, v208 quad_perm:[3,2,1,0] row_mask:0xf bank_mask:0xf
	v_mov_b32_dpp v229, v209 quad_perm:[3,2,1,0] row_mask:0xf bank_mask:0xf
	v_mov_b32_dpp v230, v210 quad_perm:[3,2,1,0] row_mask:0xf bank_mask:0xf
	v_mov_b32_dpp v231, v211 quad_perm:[3,2,1,0] row_mask:0xf bank_mask:0xf
	v_mov_b32_dpp v232, v212 quad_perm:[3,2,1,0] row_mask:0xf bank_mask:0xf
	v_mov_b32_dpp v233, v213 quad_perm:[3,2,1,0] row_mask:0xf bank_mask:0xf
	v_mov_b32_dpp v234, v214 quad_perm:[3,2,1,0] row_mask:0xf bank_mask:0xf
	v_mov_b32_dpp v235, v215 quad_perm:[3,2,1,0] row_mask:0xf bank_mask:0xf
	v_mul_f32_e32 v216, v69, v216
	v_mul_f32_e32 v217, v71, v217
	v_mul_f32_e32 v218, v73, v218
	v_mul_f32_e32 v219, v75, v219
	v_mul_f32_e32 v220, v69, v220
	v_mul_f32_e32 v221, v71, v221
	v_mul_f32_e32 v222, v73, v222
	v_mul_f32_e32 v223, v75, v223
	v_mul_f32_e32 v224, v77, v224
	v_mul_f32_e32 v225, v79, v225
	v_mul_f32_e32 v226, v81, v226
	v_mul_f32_e32 v227, v83, v227
	v_mul_f32_e32 v228, v77, v228
	v_mul_f32_e32 v229, v79, v229
	v_mul_f32_e32 v230, v81, v230
	v_mul_f32_e32 v231, v83, v231
	v_mul_f32_e32 v232, v85, v232
	v_mul_f32_e32 v233, v87, v233
	v_mul_f32_e32 v234, v89, v234
	v_mul_f32_e32 v235, v91, v235
	v_fmac_f32_e32 v216, v68, v164
	v_fmac_f32_e32 v217, v70, v165
	v_fmac_f32_e32 v218, v72, v166
	v_fmac_f32_e32 v219, v74, v167
	v_fmac_f32_e32 v220, v68, v168
	v_fmac_f32_e32 v221, v70, v169
	v_fmac_f32_e32 v222, v72, v170
	v_fmac_f32_e32 v223, v74, v171
	v_fmac_f32_e32 v224, v76, v172
	v_fmac_f32_e32 v225, v78, v173
	v_fmac_f32_e32 v226, v80, v174
	v_fmac_f32_e32 v227, v82, v175
	v_fmac_f32_e32 v228, v76, v176
	v_fmac_f32_e32 v229, v78, v177
	v_fmac_f32_e32 v230, v80, v178
	v_fmac_f32_e32 v231, v82, v179
	v_fmac_f32_e32 v232, v84, v180
	v_fmac_f32_e32 v233, v86, v181
	v_fmac_f32_e32 v234, v88, v182
	v_fmac_f32_e32 v235, v90, v183
	v_mul_f32_e32 v216, 0x3e38aa3b, v216
	v_mul_f32_e32 v217, 0x3e38aa3b, v217
	v_mul_f32_e32 v218, 0x3e38aa3b, v218
	v_mul_f32_e32 v219, 0x3e38aa3b, v219
	v_mul_f32_e32 v220, 0x3e38aa3b, v220
	v_mul_f32_e32 v221, 0x3e38aa3b, v221
	v_mul_f32_e32 v222, 0x3e38aa3b, v222
	v_mul_f32_e32 v223, 0x3e38aa3b, v223
	v_mul_f32_e32 v224, 0x3e38aa3b, v224
	v_mul_f32_e32 v225, 0x3e38aa3b, v225
	v_mul_f32_e32 v226, 0x3e38aa3b, v226
	v_mul_f32_e32 v227, 0x3e38aa3b, v227
	v_mul_f32_e32 v228, 0x3e38aa3b, v228
	v_mul_f32_e32 v229, 0x3e38aa3b, v229
	v_mul_f32_e32 v230, 0x3e38aa3b, v230
	v_mul_f32_e32 v231, 0x3e38aa3b, v231
	v_cvt_pk_bf16_f32 v28, v216, v217
	v_cvt_pk_bf16_f32 v29, v218, v219
	v_cvt_pk_bf16_f32 v30, v220, v221
	v_cvt_pk_bf16_f32 v31, v222, v223
	v_cvt_pk_bf16_f32 v32, v224, v225
	v_cvt_pk_bf16_f32 v33, v226, v227
	v_cvt_pk_bf16_f32 v34, v228, v229
	v_cvt_pk_bf16_f32 v35, v230, v231
	v_cvt_pk_bf16_f32 v36, v232, v233
	v_cvt_pk_bf16_f32 v37, v234, v235
	global_store_dwordx2 v2, v[28:29], s[14:15]
	global_store_dwordx2 v2, v[30:31], s[14:15] offset:512
	global_store_dwordx2 v3, v[32:33], s[14:15]
	global_store_dwordx2 v3, v[34:35], s[14:15] offset:512
	global_store_dwordx2 v4, v[36:37], s[14:15] offset:1024
	s_mul_i32 s24, s23, 1
	s_add_i32 s24, s24, s22
	s_cmp_lt_u32 s24, 0x2000
	s_cbranch_scc0 .Lprep_skip_L0_1
	s_waitcnt vmcnt(27)
	v_mul_f32_e32 v93, v5, v93
	v_mul_f32_e32 v95, v5, v95
	v_mul_f32_e32 v97, v5, v97
	v_mul_f32_e32 v99, v5, v99
	v_mul_f32_e32 v101, v5, v101
	v_mul_f32_e32 v103, v5, v103
	v_mul_f32_e32 v105, v5, v105
	v_mul_f32_e32 v107, v5, v107
	v_mul_f32_e32 v109, v5, v109
	v_mul_f32_e32 v111, v5, v111
	v_mul_f32_e32 v113, v5, v113
	v_mul_f32_e32 v115, v5, v115
	v_lshlrev_b32_e32 v164, 16, v38
	v_and_b32_e32 v165, 0xffff0000, v38
	v_lshlrev_b32_e32 v166, 16, v39
	v_and_b32_e32 v167, 0xffff0000, v39
	v_lshlrev_b32_e32 v168, 16, v40
	v_and_b32_e32 v169, 0xffff0000, v40
	v_lshlrev_b32_e32 v170, 16, v41
	v_and_b32_e32 v171, 0xffff0000, v41
	v_lshlrev_b32_e32 v172, 16, v42
	v_and_b32_e32 v173, 0xffff0000, v42
	v_lshlrev_b32_e32 v174, 16, v43
	v_and_b32_e32 v175, 0xffff0000, v43
	v_lshlrev_b32_e32 v176, 16, v44
	v_and_b32_e32 v177, 0xffff0000, v44
	v_lshlrev_b32_e32 v178, 16, v45
	v_and_b32_e32 v179, 0xffff0000, v45
	v_lshlrev_b32_e32 v180, 16, v46
	v_and_b32_e32 v181, 0xffff0000, v46
	v_lshlrev_b32_e32 v182, 16, v47
	v_and_b32_e32 v183, 0xffff0000, v47
	v_mul_f32_e32 v184, v164, v164
	v_fmac_f32_e32 v184, v165, v165
	v_fmac_f32_e32 v184, v166, v166
	v_fmac_f32_e32 v184, v167, v167
	v_mul_f32_e32 v185, v168, v168
	v_fmac_f32_e32 v185, v169, v169
	v_fmac_f32_e32 v185, v170, v170
	v_fmac_f32_e32 v185, v171, v171
	v_mul_f32_e32 v186, v172, v172
	v_fmac_f32_e32 v186, v173, v173
	v_fmac_f32_e32 v186, v174, v174
	v_fmac_f32_e32 v186, v175, v175
	v_mul_f32_e32 v187, v176, v176
	v_fmac_f32_e32 v187, v177, v177
	v_fmac_f32_e32 v187, v178, v178
	v_fmac_f32_e32 v187, v179, v179
	v_mul_f32_e32 v188, v180, v180
	v_fmac_f32_e32 v188, v181, v181
	v_fmac_f32_e32 v188, v182, v182
	v_fmac_f32_e32 v188, v183, v183
	v_add_f32_dpp v184, v184, v184 quad_perm:[1,0,3,2] row_mask:0xf bank_mask:0xf
	v_add_f32_dpp v185, v185, v185 quad_perm:[1,0,3,2] row_mask:0xf bank_mask:0xf
	v_add_f32_dpp v186, v186, v186 quad_perm:[1,0,3,2] row_mask:0xf bank_mask:0xf
	v_add_f32_dpp v187, v187, v187 quad_perm:[1,0,3,2] row_mask:0xf bank_mask:0xf
	v_add_f32_dpp v188, v188, v188 quad_perm:[1,0,3,2] row_mask:0xf bank_mask:0xf
	v_add_f32_dpp v184, v184, v184 quad_perm:[2,3,0,1] row_mask:0xf bank_mask:0xf
	v_add_f32_dpp v185, v185, v185 quad_perm:[2,3,0,1] row_mask:0xf bank_mask:0xf
	v_add_f32_dpp v186, v186, v186 quad_perm:[2,3,0,1] row_mask:0xf bank_mask:0xf
	v_add_f32_dpp v187, v187, v187 quad_perm:[2,3,0,1] row_mask:0xf bank_mask:0xf
	v_add_f32_dpp v188, v188, v188 quad_perm:[2,3,0,1] row_mask:0xf bank_mask:0xf
	v_add_f32_dpp v184, v184, v184 row_half_mirror row_mask:0xf bank_mask:0xf
	v_add_f32_dpp v185, v185, v185 row_half_mirror row_mask:0xf bank_mask:0xf
	v_add_f32_dpp v186, v186, v186 row_half_mirror row_mask:0xf bank_mask:0xf
	v_add_f32_dpp v187, v187, v187 row_half_mirror row_mask:0xf bank_mask:0xf
	v_add_f32_dpp v188, v188, v188 row_half_mirror row_mask:0xf bank_mask:0xf
	v_add_f32_dpp v184, v184, v184 row_mirror row_mask:0xf bank_mask:0xf
	v_add_f32_dpp v185, v185, v185 row_mirror row_mask:0xf bank_mask:0xf
	v_add_f32_dpp v186, v186, v186 row_mirror row_mask:0xf bank_mask:0xf
	v_add_f32_dpp v187, v187, v187 row_mirror row_mask:0xf bank_mask:0xf
	v_add_f32_dpp v188, v188, v188 row_mirror row_mask:0xf bank_mask:0xf
	v_fmamk_f32 v184, v184, 0x3c800000, v6
	v_fmamk_f32 v185, v185, 0x3c800000, v6
	v_fmamk_f32 v186, v186, 0x3c800000, v6
	v_fmamk_f32 v187, v187, 0x3c800000, v6
	v_fmamk_f32 v188, v188, 0x3c800000, v6
	v_rsq_f32_e32 v184, v184
	v_rsq_f32_e32 v185, v185
	v_rsq_f32_e32 v186, v186
	v_rsq_f32_e32 v187, v187
	v_rsq_f32_e32 v188, v188
	v_mul_f32_e32 v164, v184, v164
	v_mul_f32_e32 v165, v184, v165
	v_mul_f32_e32 v166, v184, v166
	v_mul_f32_e32 v167, v184, v167
	v_mul_f32_e32 v168, v185, v168
	v_mul_f32_e32 v169, v185, v169
	v_mul_f32_e32 v170, v185, v170
	v_mul_f32_e32 v171, v185, v171
	v_mul_f32_e32 v172, v186, v172
	v_mul_f32_e32 v173, v186, v173
	v_mul_f32_e32 v174, v186, v174
	v_mul_f32_e32 v175, v186, v175
	v_mul_f32_e32 v176, v187, v176
	v_mul_f32_e32 v177, v187, v177
	v_mul_f32_e32 v178, v187, v178
	v_mul_f32_e32 v179, v187, v179
	v_mul_f32_e32 v180, v188, v180
	v_mul_f32_e32 v181, v188, v181
	v_mul_f32_e32 v182, v188, v182
	v_mul_f32_e32 v183, v188, v183
	v_mul_f32_e32 v164, v12, v164
	v_mul_f32_e32 v165, v13, v165
	v_mul_f32_e32 v166, v14, v166
	v_mul_f32_e32 v167, v15, v167
	v_mul_f32_e32 v168, v12, v168
	v_mul_f32_e32 v169, v13, v169
	v_mul_f32_e32 v170, v14, v170
	v_mul_f32_e32 v171, v15, v171
	v_mul_f32_e32 v172, v12, v172
	v_mul_f32_e32 v173, v13, v173
	v_mul_f32_e32 v174, v14, v174
	v_mul_f32_e32 v175, v15, v175
	v_mul_f32_e32 v176, v12, v176
	v_mul_f32_e32 v177, v13, v177
	v_mul_f32_e32 v178, v14, v178
	v_mul_f32_e32 v179, v15, v179
	v_mul_f32_e32 v180, v16, v180
	v_mul_f32_e32 v181, v17, v181
	v_mul_f32_e32 v182, v18, v182
	v_mul_f32_e32 v183, v19, v183
	v_mov_b32_dpp v196, v164 row_half_mirror row_mask:0xf bank_mask:0xf
	v_mov_b32_dpp v197, v165 row_half_mirror row_mask:0xf bank_mask:0xf
	v_mov_b32_dpp v198, v166 row_half_mirror row_mask:0xf bank_mask:0xf
	v_mov_b32_dpp v199, v167 row_half_mirror row_mask:0xf bank_mask:0xf
	v_mov_b32_dpp v200, v168 row_half_mirror row_mask:0xf bank_mask:0xf
	v_mov_b32_dpp v201, v169 row_half_mirror row_mask:0xf bank_mask:0xf
	v_mov_b32_dpp v202, v170 row_half_mirror row_mask:0xf bank_mask:0xf
	v_mov_b32_dpp v203, v171 row_half_mirror row_mask:0xf bank_mask:0xf
	v_mov_b32_dpp v204, v172 row_half_mirror row_mask:0xf bank_mask:0xf
	v_mov_b32_dpp v205, v173 row_half_mirror row_mask:0xf bank_mask:0xf
	v_mov_b32_dpp v206, v174 row_half_mirror row_mask:0xf bank_mask:0xf
	v_mov_b32_dpp v207, v175 row_half_mirror row_mask:0xf bank_mask:0xf
	v_mov_b32_dpp v208, v176 row_half_mirror row_mask:0xf bank_mask:0xf
	v_mov_b32_dpp v209, v177 row_half_mirror row_mask:0xf bank_mask:0xf
	v_mov_b32_dpp v210, v178 row_half_mirror row_mask:0xf bank_mask:0xf
	v_mov_b32_dpp v211, v179 row_half_mirror row_mask:0xf bank_mask:0xf
	v_mov_b32_dpp v212, v180 row_half_mirror row_mask:0xf bank_mask:0xf
	v_mov_b32_dpp v213, v181 row_half_mirror row_mask:0xf bank_mask:0xf
	v_mov_b32_dpp v214, v182 row_half_mirror row_mask:0xf bank_mask:0xf
	v_mov_b32_dpp v215, v183 row_half_mirror row_mask:0xf bank_mask:0xf
	v_mov_b32_dpp v216, v196 quad_perm:[3,2,1,0] row_mask:0xf bank_mask:0xf
	v_mov_b32_dpp v217, v197 quad_perm:[3,2,1,0] row_mask:0xf bank_mask:0xf
	v_mov_b32_dpp v218, v198 quad_perm:[3,2,1,0] row_mask:0xf bank_mask:0xf
	v_mov_b32_dpp v219, v199 quad_perm:[3,2,1,0] row_mask:0xf bank_mask:0xf
	v_mov_b32_dpp v220, v200 quad_perm:[3,2,1,0] row_mask:0xf bank_mask:0xf
	v_mov_b32_dpp v221, v201 quad_perm:[3,2,1,0] row_mask:0xf bank_mask:0xf
	v_mov_b32_dpp v222, v202 quad_perm:[3,2,1,0] row_mask:0xf bank_mask:0xf
	v_mov_b32_dpp v223, v203 quad_perm:[3,2,1,0] row_mask:0xf bank_mask:0xf
	v_mov_b32_dpp v224, v204 quad_perm:[3,2,1,0] row_mask:0xf bank_mask:0xf
	v_mov_b32_dpp v225, v205 quad_perm:[3,2,1,0] row_mask:0xf bank_mask:0xf
	v_mov_b32_dpp v226, v206 quad_perm:[3,2,1,0] row_mask:0xf bank_mask:0xf
	v_mov_b32_dpp v227, v207 quad_perm:[3,2,1,0] row_mask:0xf bank_mask:0xf
	v_mov_b32_dpp v228, v208 quad_perm:[3,2,1,0] row_mask:0xf bank_mask:0xf
	v_mov_b32_dpp v229, v209 quad_perm:[3,2,1,0] row_mask:0xf bank_mask:0xf
	v_mov_b32_dpp v230, v210 quad_perm:[3,2,1,0] row_mask:0xf bank_mask:0xf
	v_mov_b32_dpp v231, v211 quad_perm:[3,2,1,0] row_mask:0xf bank_mask:0xf
	v_mov_b32_dpp v232, v212 quad_perm:[3,2,1,0] row_mask:0xf bank_mask:0xf
	v_mov_b32_dpp v233, v213 quad_perm:[3,2,1,0] row_mask:0xf bank_mask:0xf
	v_mov_b32_dpp v234, v214 quad_perm:[3,2,1,0] row_mask:0xf bank_mask:0xf
	v_mov_b32_dpp v235, v215 quad_perm:[3,2,1,0] row_mask:0xf bank_mask:0xf
	v_mul_f32_e32 v216, v93, v216
	v_mul_f32_e32 v217, v95, v217
	v_mul_f32_e32 v218, v97, v218
	v_mul_f32_e32 v219, v99, v219
	v_mul_f32_e32 v220, v93, v220
	v_mul_f32_e32 v221, v95, v221
	v_mul_f32_e32 v222, v97, v222
	v_mul_f32_e32 v223, v99, v223
	v_mul_f32_e32 v224, v101, v224
	v_mul_f32_e32 v225, v103, v225
	v_mul_f32_e32 v226, v105, v226
	v_mul_f32_e32 v227, v107, v227
	v_mul_f32_e32 v228, v101, v228
	v_mul_f32_e32 v229, v103, v229
	v_mul_f32_e32 v230, v105, v230
	v_mul_f32_e32 v231, v107, v231
	v_mul_f32_e32 v232, v109, v232
	v_mul_f32_e32 v233, v111, v233
	v_mul_f32_e32 v234, v113, v234
	v_mul_f32_e32 v235, v115, v235
	v_fmac_f32_e32 v216, v92, v164
	v_fmac_f32_e32 v217, v94, v165
	v_fmac_f32_e32 v218, v96, v166
	v_fmac_f32_e32 v219, v98, v167
	v_fmac_f32_e32 v220, v92, v168
	v_fmac_f32_e32 v221, v94, v169
	v_fmac_f32_e32 v222, v96, v170
	v_fmac_f32_e32 v223, v98, v171
	v_fmac_f32_e32 v224, v100, v172
	v_fmac_f32_e32 v225, v102, v173
	v_fmac_f32_e32 v226, v104, v174
	v_fmac_f32_e32 v227, v106, v175
	v_fmac_f32_e32 v228, v100, v176
	v_fmac_f32_e32 v229, v102, v177
	v_fmac_f32_e32 v230, v104, v178
	v_fmac_f32_e32 v231, v106, v179
	v_fmac_f32_e32 v232, v108, v180
	v_fmac_f32_e32 v233, v110, v181
	v_fmac_f32_e32 v234, v112, v182
	v_fmac_f32_e32 v235, v114, v183
	v_mul_f32_e32 v216, 0x3e38aa3b, v216
	v_mul_f32_e32 v217, 0x3e38aa3b, v217
	v_mul_f32_e32 v218, 0x3e38aa3b, v218
	v_mul_f32_e32 v219, 0x3e38aa3b, v219
	v_mul_f32_e32 v220, 0x3e38aa3b, v220
	v_mul_f32_e32 v221, 0x3e38aa3b, v221
	v_mul_f32_e32 v222, 0x3e38aa3b, v222
	v_mul_f32_e32 v223, 0x3e38aa3b, v223
	v_mul_f32_e32 v224, 0x3e38aa3b, v224
	v_mul_f32_e32 v225, 0x3e38aa3b, v225
	v_mul_f32_e32 v226, 0x3e38aa3b, v226
	v_mul_f32_e32 v227, 0x3e38aa3b, v227
	v_mul_f32_e32 v228, 0x3e38aa3b, v228
	v_mul_f32_e32 v229, 0x3e38aa3b, v229
	v_mul_f32_e32 v230, 0x3e38aa3b, v230
	v_mul_f32_e32 v231, 0x3e38aa3b, v231
	v_cvt_pk_bf16_f32 v38, v216, v217
	v_cvt_pk_bf16_f32 v39, v218, v219
	v_cvt_pk_bf16_f32 v40, v220, v221
	v_cvt_pk_bf16_f32 v41, v222, v223
	v_cvt_pk_bf16_f32 v42, v224, v225
	v_cvt_pk_bf16_f32 v43, v226, v227
	v_cvt_pk_bf16_f32 v44, v228, v229
	v_cvt_pk_bf16_f32 v45, v230, v231
	v_cvt_pk_bf16_f32 v46, v232, v233
	v_cvt_pk_bf16_f32 v47, v234, v235
	global_store_dwordx2 v2, v[38:39], s[16:17]
	global_store_dwordx2 v2, v[40:41], s[16:17] offset:512
	global_store_dwordx2 v3, v[42:43], s[16:17]
	global_store_dwordx2 v3, v[44:45], s[16:17] offset:512
	global_store_dwordx2 v4, v[46:47], s[16:17] offset:1024
.Lprep_skip_L0_1:
	s_mul_i32 s24, s23, 2
	s_add_i32 s24, s24, s22
	s_cmp_lt_u32 s24, 0x2000
	s_cbranch_scc0 .Lprep_skip_L0_2
	s_waitcnt vmcnt(21)
	v_mul_f32_e32 v117, v5, v117
	v_mul_f32_e32 v119, v5, v119
	v_mul_f32_e32 v121, v5, v121
	v_mul_f32_e32 v123, v5, v123
	v_mul_f32_e32 v125, v5, v125
	v_mul_f32_e32 v127, v5, v127
	v_mul_f32_e32 v129, v5, v129
	v_mul_f32_e32 v131, v5, v131
	v_mul_f32_e32 v133, v5, v133
	v_mul_f32_e32 v135, v5, v135
	v_mul_f32_e32 v137, v5, v137
	v_mul_f32_e32 v139, v5, v139
	v_lshlrev_b32_e32 v164, 16, v48
	v_and_b32_e32 v165, 0xffff0000, v48
	v_lshlrev_b32_e32 v166, 16, v49
	v_and_b32_e32 v167, 0xffff0000, v49
	v_lshlrev_b32_e32 v168, 16, v50
	v_and_b32_e32 v169, 0xffff0000, v50
	v_lshlrev_b32_e32 v170, 16, v51
	v_and_b32_e32 v171, 0xffff0000, v51
	v_lshlrev_b32_e32 v172, 16, v52
	v_and_b32_e32 v173, 0xffff0000, v52
	v_lshlrev_b32_e32 v174, 16, v53
	v_and_b32_e32 v175, 0xffff0000, v53
	v_lshlrev_b32_e32 v176, 16, v54
	v_and_b32_e32 v177, 0xffff0000, v54
	v_lshlrev_b32_e32 v178, 16, v55
	v_and_b32_e32 v179, 0xffff0000, v55
	v_lshlrev_b32_e32 v180, 16, v56
	v_and_b32_e32 v181, 0xffff0000, v56
	v_lshlrev_b32_e32 v182, 16, v57
	v_and_b32_e32 v183, 0xffff0000, v57
	v_mul_f32_e32 v184, v164, v164
	v_fmac_f32_e32 v184, v165, v165
	v_fmac_f32_e32 v184, v166, v166
	v_fmac_f32_e32 v184, v167, v167
	v_mul_f32_e32 v185, v168, v168
	v_fmac_f32_e32 v185, v169, v169
	v_fmac_f32_e32 v185, v170, v170
	v_fmac_f32_e32 v185, v171, v171
	v_mul_f32_e32 v186, v172, v172
	v_fmac_f32_e32 v186, v173, v173
	v_fmac_f32_e32 v186, v174, v174
	v_fmac_f32_e32 v186, v175, v175
	v_mul_f32_e32 v187, v176, v176
	v_fmac_f32_e32 v187, v177, v177
	v_fmac_f32_e32 v187, v178, v178
	v_fmac_f32_e32 v187, v179, v179
	v_mul_f32_e32 v188, v180, v180
	v_fmac_f32_e32 v188, v181, v181
	v_fmac_f32_e32 v188, v182, v182
	v_fmac_f32_e32 v188, v183, v183
	v_add_f32_dpp v184, v184, v184 quad_perm:[1,0,3,2] row_mask:0xf bank_mask:0xf
	v_add_f32_dpp v185, v185, v185 quad_perm:[1,0,3,2] row_mask:0xf bank_mask:0xf
	v_add_f32_dpp v186, v186, v186 quad_perm:[1,0,3,2] row_mask:0xf bank_mask:0xf
	v_add_f32_dpp v187, v187, v187 quad_perm:[1,0,3,2] row_mask:0xf bank_mask:0xf
	v_add_f32_dpp v188, v188, v188 quad_perm:[1,0,3,2] row_mask:0xf bank_mask:0xf
	v_add_f32_dpp v184, v184, v184 quad_perm:[2,3,0,1] row_mask:0xf bank_mask:0xf
	v_add_f32_dpp v185, v185, v185 quad_perm:[2,3,0,1] row_mask:0xf bank_mask:0xf
	v_add_f32_dpp v186, v186, v186 quad_perm:[2,3,0,1] row_mask:0xf bank_mask:0xf
	v_add_f32_dpp v187, v187, v187 quad_perm:[2,3,0,1] row_mask:0xf bank_mask:0xf
	v_add_f32_dpp v188, v188, v188 quad_perm:[2,3,0,1] row_mask:0xf bank_mask:0xf
	v_add_f32_dpp v184, v184, v184 row_half_mirror row_mask:0xf bank_mask:0xf
	v_add_f32_dpp v185, v185, v185 row_half_mirror row_mask:0xf bank_mask:0xf
	v_add_f32_dpp v186, v186, v186 row_half_mirror row_mask:0xf bank_mask:0xf
	v_add_f32_dpp v187, v187, v187 row_half_mirror row_mask:0xf bank_mask:0xf
	v_add_f32_dpp v188, v188, v188 row_half_mirror row_mask:0xf bank_mask:0xf
	v_add_f32_dpp v184, v184, v184 row_mirror row_mask:0xf bank_mask:0xf
	v_add_f32_dpp v185, v185, v185 row_mirror row_mask:0xf bank_mask:0xf
	v_add_f32_dpp v186, v186, v186 row_mirror row_mask:0xf bank_mask:0xf
	v_add_f32_dpp v187, v187, v187 row_mirror row_mask:0xf bank_mask:0xf
	v_add_f32_dpp v188, v188, v188 row_mirror row_mask:0xf bank_mask:0xf
	v_fmamk_f32 v184, v184, 0x3c800000, v6
	v_fmamk_f32 v185, v185, 0x3c800000, v6
	v_fmamk_f32 v186, v186, 0x3c800000, v6
	v_fmamk_f32 v187, v187, 0x3c800000, v6
	v_fmamk_f32 v188, v188, 0x3c800000, v6
	v_rsq_f32_e32 v184, v184
	v_rsq_f32_e32 v185, v185
	v_rsq_f32_e32 v186, v186
	v_rsq_f32_e32 v187, v187
	v_rsq_f32_e32 v188, v188
	v_mul_f32_e32 v164, v184, v164
	v_mul_f32_e32 v165, v184, v165
	v_mul_f32_e32 v166, v184, v166
	v_mul_f32_e32 v167, v184, v167
	v_mul_f32_e32 v168, v185, v168
	v_mul_f32_e32 v169, v185, v169
	v_mul_f32_e32 v170, v185, v170
	v_mul_f32_e32 v171, v185, v171
	v_mul_f32_e32 v172, v186, v172
	v_mul_f32_e32 v173, v186, v173
	v_mul_f32_e32 v174, v186, v174
	v_mul_f32_e32 v175, v186, v175
	v_mul_f32_e32 v176, v187, v176
	v_mul_f32_e32 v177, v187, v177
	v_mul_f32_e32 v178, v187, v178
	v_mul_f32_e32 v179, v187, v179
	v_mul_f32_e32 v180, v188, v180
	v_mul_f32_e32 v181, v188, v181
	v_mul_f32_e32 v182, v188, v182
	v_mul_f32_e32 v183, v188, v183
	v_mul_f32_e32 v164, v12, v164
	v_mul_f32_e32 v165, v13, v165
	v_mul_f32_e32 v166, v14, v166
	v_mul_f32_e32 v167, v15, v167
	v_mul_f32_e32 v168, v12, v168
	v_mul_f32_e32 v169, v13, v169
	v_mul_f32_e32 v170, v14, v170
	v_mul_f32_e32 v171, v15, v171
	v_mul_f32_e32 v172, v12, v172
	v_mul_f32_e32 v173, v13, v173
	v_mul_f32_e32 v174, v14, v174
	v_mul_f32_e32 v175, v15, v175
	v_mul_f32_e32 v176, v12, v176
	v_mul_f32_e32 v177, v13, v177
	v_mul_f32_e32 v178, v14, v178
	v_mul_f32_e32 v179, v15, v179
	v_mul_f32_e32 v180, v16, v180
	v_mul_f32_e32 v181, v17, v181
	v_mul_f32_e32 v182, v18, v182
	v_mul_f32_e32 v183, v19, v183
	v_mov_b32_dpp v196, v164 row_half_mirror row_mask:0xf bank_mask:0xf
	v_mov_b32_dpp v197, v165 row_half_mirror row_mask:0xf bank_mask:0xf
	v_mov_b32_dpp v198, v166 row_half_mirror row_mask:0xf bank_mask:0xf
	v_mov_b32_dpp v199, v167 row_half_mirror row_mask:0xf bank_mask:0xf
	v_mov_b32_dpp v200, v168 row_half_mirror row_mask:0xf bank_mask:0xf
	v_mov_b32_dpp v201, v169 row_half_mirror row_mask:0xf bank_mask:0xf
	v_mov_b32_dpp v202, v170 row_half_mirror row_mask:0xf bank_mask:0xf
	v_mov_b32_dpp v203, v171 row_half_mirror row_mask:0xf bank_mask:0xf
	v_mov_b32_dpp v204, v172 row_half_mirror row_mask:0xf bank_mask:0xf
	v_mov_b32_dpp v205, v173 row_half_mirror row_mask:0xf bank_mask:0xf
	v_mov_b32_dpp v206, v174 row_half_mirror row_mask:0xf bank_mask:0xf
	v_mov_b32_dpp v207, v175 row_half_mirror row_mask:0xf bank_mask:0xf
	v_mov_b32_dpp v208, v176 row_half_mirror row_mask:0xf bank_mask:0xf
	v_mov_b32_dpp v209, v177 row_half_mirror row_mask:0xf bank_mask:0xf
	v_mov_b32_dpp v210, v178 row_half_mirror row_mask:0xf bank_mask:0xf
	v_mov_b32_dpp v211, v179 row_half_mirror row_mask:0xf bank_mask:0xf
	v_mov_b32_dpp v212, v180 row_half_mirror row_mask:0xf bank_mask:0xf
	v_mov_b32_dpp v213, v181 row_half_mirror row_mask:0xf bank_mask:0xf
	v_mov_b32_dpp v214, v182 row_half_mirror row_mask:0xf bank_mask:0xf
	v_mov_b32_dpp v215, v183 row_half_mirror row_mask:0xf bank_mask:0xf
	v_mov_b32_dpp v216, v196 quad_perm:[3,2,1,0] row_mask:0xf bank_mask:0xf
	v_mov_b32_dpp v217, v197 quad_perm:[3,2,1,0] row_mask:0xf bank_mask:0xf
	v_mov_b32_dpp v218, v198 quad_perm:[3,2,1,0] row_mask:0xf bank_mask:0xf
	v_mov_b32_dpp v219, v199 quad_perm:[3,2,1,0] row_mask:0xf bank_mask:0xf
	v_mov_b32_dpp v220, v200 quad_perm:[3,2,1,0] row_mask:0xf bank_mask:0xf
	v_mov_b32_dpp v221, v201 quad_perm:[3,2,1,0] row_mask:0xf bank_mask:0xf
	v_mov_b32_dpp v222, v202 quad_perm:[3,2,1,0] row_mask:0xf bank_mask:0xf
	v_mov_b32_dpp v223, v203 quad_perm:[3,2,1,0] row_mask:0xf bank_mask:0xf
	v_mov_b32_dpp v224, v204 quad_perm:[3,2,1,0] row_mask:0xf bank_mask:0xf
	v_mov_b32_dpp v225, v205 quad_perm:[3,2,1,0] row_mask:0xf bank_mask:0xf
	v_mov_b32_dpp v226, v206 quad_perm:[3,2,1,0] row_mask:0xf bank_mask:0xf
	v_mov_b32_dpp v227, v207 quad_perm:[3,2,1,0] row_mask:0xf bank_mask:0xf
	v_mov_b32_dpp v228, v208 quad_perm:[3,2,1,0] row_mask:0xf bank_mask:0xf
	v_mov_b32_dpp v229, v209 quad_perm:[3,2,1,0] row_mask:0xf bank_mask:0xf
	v_mov_b32_dpp v230, v210 quad_perm:[3,2,1,0] row_mask:0xf bank_mask:0xf
	v_mov_b32_dpp v231, v211 quad_perm:[3,2,1,0] row_mask:0xf bank_mask:0xf
	v_mov_b32_dpp v232, v212 quad_perm:[3,2,1,0] row_mask:0xf bank_mask:0xf
	v_mov_b32_dpp v233, v213 quad_perm:[3,2,1,0] row_mask:0xf bank_mask:0xf
	v_mov_b32_dpp v234, v214 quad_perm:[3,2,1,0] row_mask:0xf bank_mask:0xf
	v_mov_b32_dpp v235, v215 quad_perm:[3,2,1,0] row_mask:0xf bank_mask:0xf
	v_mul_f32_e32 v216, v117, v216
	v_mul_f32_e32 v217, v119, v217
	v_mul_f32_e32 v218, v121, v218
	v_mul_f32_e32 v219, v123, v219
	v_mul_f32_e32 v220, v117, v220
	v_mul_f32_e32 v221, v119, v221
	v_mul_f32_e32 v222, v121, v222
	v_mul_f32_e32 v223, v123, v223
	v_mul_f32_e32 v224, v125, v224
	v_mul_f32_e32 v225, v127, v225
	v_mul_f32_e32 v226, v129, v226
	v_mul_f32_e32 v227, v131, v227
	v_mul_f32_e32 v228, v125, v228
	v_mul_f32_e32 v229, v127, v229
	v_mul_f32_e32 v230, v129, v230
	v_mul_f32_e32 v231, v131, v231
	v_mul_f32_e32 v232, v133, v232
	v_mul_f32_e32 v233, v135, v233
	v_mul_f32_e32 v234, v137, v234
	v_mul_f32_e32 v235, v139, v235
	v_fmac_f32_e32 v216, v116, v164
	v_fmac_f32_e32 v217, v118, v165
	v_fmac_f32_e32 v218, v120, v166
	v_fmac_f32_e32 v219, v122, v167
	v_fmac_f32_e32 v220, v116, v168
	v_fmac_f32_e32 v221, v118, v169
	v_fmac_f32_e32 v222, v120, v170
	v_fmac_f32_e32 v223, v122, v171
	v_fmac_f32_e32 v224, v124, v172
	v_fmac_f32_e32 v225, v126, v173
	v_fmac_f32_e32 v226, v128, v174
	v_fmac_f32_e32 v227, v130, v175
	v_fmac_f32_e32 v228, v124, v176
	v_fmac_f32_e32 v229, v126, v177
	v_fmac_f32_e32 v230, v128, v178
	v_fmac_f32_e32 v231, v130, v179
	v_fmac_f32_e32 v232, v132, v180
	v_fmac_f32_e32 v233, v134, v181
	v_fmac_f32_e32 v234, v136, v182
	v_fmac_f32_e32 v235, v138, v183
	v_mul_f32_e32 v216, 0x3e38aa3b, v216
	v_mul_f32_e32 v217, 0x3e38aa3b, v217
	v_mul_f32_e32 v218, 0x3e38aa3b, v218
	v_mul_f32_e32 v219, 0x3e38aa3b, v219
	v_mul_f32_e32 v220, 0x3e38aa3b, v220
	v_mul_f32_e32 v221, 0x3e38aa3b, v221
	v_mul_f32_e32 v222, 0x3e38aa3b, v222
	v_mul_f32_e32 v223, 0x3e38aa3b, v223
	v_mul_f32_e32 v224, 0x3e38aa3b, v224
	v_mul_f32_e32 v225, 0x3e38aa3b, v225
	v_mul_f32_e32 v226, 0x3e38aa3b, v226
	v_mul_f32_e32 v227, 0x3e38aa3b, v227
	v_mul_f32_e32 v228, 0x3e38aa3b, v228
	v_mul_f32_e32 v229, 0x3e38aa3b, v229
	v_mul_f32_e32 v230, 0x3e38aa3b, v230
	v_mul_f32_e32 v231, 0x3e38aa3b, v231
	v_cvt_pk_bf16_f32 v48, v216, v217
	v_cvt_pk_bf16_f32 v49, v218, v219
	v_cvt_pk_bf16_f32 v50, v220, v221
	v_cvt_pk_bf16_f32 v51, v222, v223
	v_cvt_pk_bf16_f32 v52, v224, v225
	v_cvt_pk_bf16_f32 v53, v226, v227
	v_cvt_pk_bf16_f32 v54, v228, v229
	v_cvt_pk_bf16_f32 v55, v230, v231
	v_cvt_pk_bf16_f32 v56, v232, v233
	v_cvt_pk_bf16_f32 v57, v234, v235
	global_store_dwordx2 v2, v[48:49], s[18:19]
	global_store_dwordx2 v2, v[50:51], s[18:19] offset:512
	global_store_dwordx2 v3, v[52:53], s[18:19]
	global_store_dwordx2 v3, v[54:55], s[18:19] offset:512
	global_store_dwordx2 v4, v[56:57], s[18:19] offset:1024
.Lprep_skip_L0_2:
	s_mul_i32 s24, s23, 3
	s_add_i32 s24, s24, s22
	s_cmp_lt_u32 s24, 0x2000
	s_cbranch_scc0 .Lprep_skip_L0_3
	s_waitcnt vmcnt(15)
	v_mul_f32_e32 v141, v5, v141
	v_mul_f32_e32 v143, v5, v143
	v_mul_f32_e32 v145, v5, v145
	v_mul_f32_e32 v147, v5, v147
	v_mul_f32_e32 v149, v5, v149
	v_mul_f32_e32 v151, v5, v151
	v_mul_f32_e32 v153, v5, v153
	v_mul_f32_e32 v155, v5, v155
	v_mul_f32_e32 v157, v5, v157
	v_mul_f32_e32 v159, v5, v159
	v_mul_f32_e32 v161, v5, v161
	v_mul_f32_e32 v163, v5, v163
	v_lshlrev_b32_e32 v164, 16, v58
	v_and_b32_e32 v165, 0xffff0000, v58
	v_lshlrev_b32_e32 v166, 16, v59
	v_and_b32_e32 v167, 0xffff0000, v59
	v_lshlrev_b32_e32 v168, 16, v60
	v_and_b32_e32 v169, 0xffff0000, v60
	v_lshlrev_b32_e32 v170, 16, v61
	v_and_b32_e32 v171, 0xffff0000, v61
	v_lshlrev_b32_e32 v172, 16, v62
	v_and_b32_e32 v173, 0xffff0000, v62
	v_lshlrev_b32_e32 v174, 16, v63
	v_and_b32_e32 v175, 0xffff0000, v63
	v_lshlrev_b32_e32 v176, 16, v64
	v_and_b32_e32 v177, 0xffff0000, v64
	v_lshlrev_b32_e32 v178, 16, v65
	v_and_b32_e32 v179, 0xffff0000, v65
	v_lshlrev_b32_e32 v180, 16, v66
	v_and_b32_e32 v181, 0xffff0000, v66
	v_lshlrev_b32_e32 v182, 16, v67
	v_and_b32_e32 v183, 0xffff0000, v67
	v_mul_f32_e32 v184, v164, v164
	v_fmac_f32_e32 v184, v165, v165
	v_fmac_f32_e32 v184, v166, v166
	v_fmac_f32_e32 v184, v167, v167
	v_mul_f32_e32 v185, v168, v168
	v_fmac_f32_e32 v185, v169, v169
	v_fmac_f32_e32 v185, v170, v170
	v_fmac_f32_e32 v185, v171, v171
	v_mul_f32_e32 v186, v172, v172
	v_fmac_f32_e32 v186, v173, v173
	v_fmac_f32_e32 v186, v174, v174
	v_fmac_f32_e32 v186, v175, v175
	v_mul_f32_e32 v187, v176, v176
	v_fmac_f32_e32 v187, v177, v177
	v_fmac_f32_e32 v187, v178, v178
	v_fmac_f32_e32 v187, v179, v179
	v_mul_f32_e32 v188, v180, v180
	v_fmac_f32_e32 v188, v181, v181
	v_fmac_f32_e32 v188, v182, v182
	v_fmac_f32_e32 v188, v183, v183
	v_add_f32_dpp v184, v184, v184 quad_perm:[1,0,3,2] row_mask:0xf bank_mask:0xf
	v_add_f32_dpp v185, v185, v185 quad_perm:[1,0,3,2] row_mask:0xf bank_mask:0xf
	v_add_f32_dpp v186, v186, v186 quad_perm:[1,0,3,2] row_mask:0xf bank_mask:0xf
	v_add_f32_dpp v187, v187, v187 quad_perm:[1,0,3,2] row_mask:0xf bank_mask:0xf
	v_add_f32_dpp v188, v188, v188 quad_perm:[1,0,3,2] row_mask:0xf bank_mask:0xf
	v_add_f32_dpp v184, v184, v184 quad_perm:[2,3,0,1] row_mask:0xf bank_mask:0xf
	v_add_f32_dpp v185, v185, v185 quad_perm:[2,3,0,1] row_mask:0xf bank_mask:0xf
	v_add_f32_dpp v186, v186, v186 quad_perm:[2,3,0,1] row_mask:0xf bank_mask:0xf
	v_add_f32_dpp v187, v187, v187 quad_perm:[2,3,0,1] row_mask:0xf bank_mask:0xf
	v_add_f32_dpp v188, v188, v188 quad_perm:[2,3,0,1] row_mask:0xf bank_mask:0xf
	v_add_f32_dpp v184, v184, v184 row_half_mirror row_mask:0xf bank_mask:0xf
	v_add_f32_dpp v185, v185, v185 row_half_mirror row_mask:0xf bank_mask:0xf
	v_add_f32_dpp v186, v186, v186 row_half_mirror row_mask:0xf bank_mask:0xf
	v_add_f32_dpp v187, v187, v187 row_half_mirror row_mask:0xf bank_mask:0xf
	v_add_f32_dpp v188, v188, v188 row_half_mirror row_mask:0xf bank_mask:0xf
	v_add_f32_dpp v184, v184, v184 row_mirror row_mask:0xf bank_mask:0xf
	v_add_f32_dpp v185, v185, v185 row_mirror row_mask:0xf bank_mask:0xf
	v_add_f32_dpp v186, v186, v186 row_mirror row_mask:0xf bank_mask:0xf
	v_add_f32_dpp v187, v187, v187 row_mirror row_mask:0xf bank_mask:0xf
	v_add_f32_dpp v188, v188, v188 row_mirror row_mask:0xf bank_mask:0xf
	v_fmamk_f32 v184, v184, 0x3c800000, v6
	v_fmamk_f32 v185, v185, 0x3c800000, v6
	v_fmamk_f32 v186, v186, 0x3c800000, v6
	v_fmamk_f32 v187, v187, 0x3c800000, v6
	v_fmamk_f32 v188, v188, 0x3c800000, v6
	v_rsq_f32_e32 v184, v184
	v_rsq_f32_e32 v185, v185
	v_rsq_f32_e32 v186, v186
	v_rsq_f32_e32 v187, v187
	v_rsq_f32_e32 v188, v188
	v_mul_f32_e32 v164, v184, v164
	v_mul_f32_e32 v165, v184, v165
	v_mul_f32_e32 v166, v184, v166
	v_mul_f32_e32 v167, v184, v167
	v_mul_f32_e32 v168, v185, v168
	v_mul_f32_e32 v169, v185, v169
	v_mul_f32_e32 v170, v185, v170
	v_mul_f32_e32 v171, v185, v171
	v_mul_f32_e32 v172, v186, v172
	v_mul_f32_e32 v173, v186, v173
	v_mul_f32_e32 v174, v186, v174
	v_mul_f32_e32 v175, v186, v175
	v_mul_f32_e32 v176, v187, v176
	v_mul_f32_e32 v177, v187, v177
	v_mul_f32_e32 v178, v187, v178
	v_mul_f32_e32 v179, v187, v179
	v_mul_f32_e32 v180, v188, v180
	v_mul_f32_e32 v181, v188, v181
	v_mul_f32_e32 v182, v188, v182
	v_mul_f32_e32 v183, v188, v183
	v_mul_f32_e32 v164, v12, v164
	v_mul_f32_e32 v165, v13, v165
	v_mul_f32_e32 v166, v14, v166
	v_mul_f32_e32 v167, v15, v167
	v_mul_f32_e32 v168, v12, v168
	v_mul_f32_e32 v169, v13, v169
	v_mul_f32_e32 v170, v14, v170
	v_mul_f32_e32 v171, v15, v171
	v_mul_f32_e32 v172, v12, v172
	v_mul_f32_e32 v173, v13, v173
	v_mul_f32_e32 v174, v14, v174
	v_mul_f32_e32 v175, v15, v175
	v_mul_f32_e32 v176, v12, v176
	v_mul_f32_e32 v177, v13, v177
	v_mul_f32_e32 v178, v14, v178
	v_mul_f32_e32 v179, v15, v179
	v_mul_f32_e32 v180, v16, v180
	v_mul_f32_e32 v181, v17, v181
	v_mul_f32_e32 v182, v18, v182
	v_mul_f32_e32 v183, v19, v183
	v_mov_b32_dpp v196, v164 row_half_mirror row_mask:0xf bank_mask:0xf
	v_mov_b32_dpp v197, v165 row_half_mirror row_mask:0xf bank_mask:0xf
	v_mov_b32_dpp v198, v166 row_half_mirror row_mask:0xf bank_mask:0xf
	v_mov_b32_dpp v199, v167 row_half_mirror row_mask:0xf bank_mask:0xf
	v_mov_b32_dpp v200, v168 row_half_mirror row_mask:0xf bank_mask:0xf
	v_mov_b32_dpp v201, v169 row_half_mirror row_mask:0xf bank_mask:0xf
	v_mov_b32_dpp v202, v170 row_half_mirror row_mask:0xf bank_mask:0xf
	v_mov_b32_dpp v203, v171 row_half_mirror row_mask:0xf bank_mask:0xf
	v_mov_b32_dpp v204, v172 row_half_mirror row_mask:0xf bank_mask:0xf
	v_mov_b32_dpp v205, v173 row_half_mirror row_mask:0xf bank_mask:0xf
	v_mov_b32_dpp v206, v174 row_half_mirror row_mask:0xf bank_mask:0xf
	v_mov_b32_dpp v207, v175 row_half_mirror row_mask:0xf bank_mask:0xf
	v_mov_b32_dpp v208, v176 row_half_mirror row_mask:0xf bank_mask:0xf
	v_mov_b32_dpp v209, v177 row_half_mirror row_mask:0xf bank_mask:0xf
	v_mov_b32_dpp v210, v178 row_half_mirror row_mask:0xf bank_mask:0xf
	v_mov_b32_dpp v211, v179 row_half_mirror row_mask:0xf bank_mask:0xf
	v_mov_b32_dpp v212, v180 row_half_mirror row_mask:0xf bank_mask:0xf
	v_mov_b32_dpp v213, v181 row_half_mirror row_mask:0xf bank_mask:0xf
	v_mov_b32_dpp v214, v182 row_half_mirror row_mask:0xf bank_mask:0xf
	v_mov_b32_dpp v215, v183 row_half_mirror row_mask:0xf bank_mask:0xf
	v_mov_b32_dpp v216, v196 quad_perm:[3,2,1,0] row_mask:0xf bank_mask:0xf
	v_mov_b32_dpp v217, v197 quad_perm:[3,2,1,0] row_mask:0xf bank_mask:0xf
	v_mov_b32_dpp v218, v198 quad_perm:[3,2,1,0] row_mask:0xf bank_mask:0xf
	v_mov_b32_dpp v219, v199 quad_perm:[3,2,1,0] row_mask:0xf bank_mask:0xf
	v_mov_b32_dpp v220, v200 quad_perm:[3,2,1,0] row_mask:0xf bank_mask:0xf
	v_mov_b32_dpp v221, v201 quad_perm:[3,2,1,0] row_mask:0xf bank_mask:0xf
	v_mov_b32_dpp v222, v202 quad_perm:[3,2,1,0] row_mask:0xf bank_mask:0xf
	v_mov_b32_dpp v223, v203 quad_perm:[3,2,1,0] row_mask:0xf bank_mask:0xf
	v_mov_b32_dpp v224, v204 quad_perm:[3,2,1,0] row_mask:0xf bank_mask:0xf
	v_mov_b32_dpp v225, v205 quad_perm:[3,2,1,0] row_mask:0xf bank_mask:0xf
	v_mov_b32_dpp v226, v206 quad_perm:[3,2,1,0] row_mask:0xf bank_mask:0xf
	v_mov_b32_dpp v227, v207 quad_perm:[3,2,1,0] row_mask:0xf bank_mask:0xf
	v_mov_b32_dpp v228, v208 quad_perm:[3,2,1,0] row_mask:0xf bank_mask:0xf
	v_mov_b32_dpp v229, v209 quad_perm:[3,2,1,0] row_mask:0xf bank_mask:0xf
	v_mov_b32_dpp v230, v210 quad_perm:[3,2,1,0] row_mask:0xf bank_mask:0xf
	v_mov_b32_dpp v231, v211 quad_perm:[3,2,1,0] row_mask:0xf bank_mask:0xf
	v_mov_b32_dpp v232, v212 quad_perm:[3,2,1,0] row_mask:0xf bank_mask:0xf
	v_mov_b32_dpp v233, v213 quad_perm:[3,2,1,0] row_mask:0xf bank_mask:0xf
	v_mov_b32_dpp v234, v214 quad_perm:[3,2,1,0] row_mask:0xf bank_mask:0xf
	v_mov_b32_dpp v235, v215 quad_perm:[3,2,1,0] row_mask:0xf bank_mask:0xf
	v_mul_f32_e32 v216, v141, v216
	v_mul_f32_e32 v217, v143, v217
	v_mul_f32_e32 v218, v145, v218
	v_mul_f32_e32 v219, v147, v219
	v_mul_f32_e32 v220, v141, v220
	v_mul_f32_e32 v221, v143, v221
	v_mul_f32_e32 v222, v145, v222
	v_mul_f32_e32 v223, v147, v223
	v_mul_f32_e32 v224, v149, v224
	v_mul_f32_e32 v225, v151, v225
	v_mul_f32_e32 v226, v153, v226
	v_mul_f32_e32 v227, v155, v227
	v_mul_f32_e32 v228, v149, v228
	v_mul_f32_e32 v229, v151, v229
	v_mul_f32_e32 v230, v153, v230
	v_mul_f32_e32 v231, v155, v231
	v_mul_f32_e32 v232, v157, v232
	v_mul_f32_e32 v233, v159, v233
	v_mul_f32_e32 v234, v161, v234
	v_mul_f32_e32 v235, v163, v235
	v_fmac_f32_e32 v216, v140, v164
	v_fmac_f32_e32 v217, v142, v165
	v_fmac_f32_e32 v218, v144, v166
	v_fmac_f32_e32 v219, v146, v167
	v_fmac_f32_e32 v220, v140, v168
	v_fmac_f32_e32 v221, v142, v169
	v_fmac_f32_e32 v222, v144, v170
	v_fmac_f32_e32 v223, v146, v171
	v_fmac_f32_e32 v224, v148, v172
	v_fmac_f32_e32 v225, v150, v173
	v_fmac_f32_e32 v226, v152, v174
	v_fmac_f32_e32 v227, v154, v175
	v_fmac_f32_e32 v228, v148, v176
	v_fmac_f32_e32 v229, v150, v177
	v_fmac_f32_e32 v230, v152, v178
	v_fmac_f32_e32 v231, v154, v179
	v_fmac_f32_e32 v232, v156, v180
	v_fmac_f32_e32 v233, v158, v181
	v_fmac_f32_e32 v234, v160, v182
	v_fmac_f32_e32 v235, v162, v183
	v_mul_f32_e32 v216, 0x3e38aa3b, v216
	v_mul_f32_e32 v217, 0x3e38aa3b, v217
	v_mul_f32_e32 v218, 0x3e38aa3b, v218
	v_mul_f32_e32 v219, 0x3e38aa3b, v219
	v_mul_f32_e32 v220, 0x3e38aa3b, v220
	v_mul_f32_e32 v221, 0x3e38aa3b, v221
	v_mul_f32_e32 v222, 0x3e38aa3b, v222
	v_mul_f32_e32 v223, 0x3e38aa3b, v223
	v_mul_f32_e32 v224, 0x3e38aa3b, v224
	v_mul_f32_e32 v225, 0x3e38aa3b, v225
	v_mul_f32_e32 v226, 0x3e38aa3b, v226
	v_mul_f32_e32 v227, 0x3e38aa3b, v227
	v_mul_f32_e32 v228, 0x3e38aa3b, v228
	v_mul_f32_e32 v229, 0x3e38aa3b, v229
	v_mul_f32_e32 v230, 0x3e38aa3b, v230
	v_mul_f32_e32 v231, 0x3e38aa3b, v231
	v_cvt_pk_bf16_f32 v58, v216, v217
	v_cvt_pk_bf16_f32 v59, v218, v219
	v_cvt_pk_bf16_f32 v60, v220, v221
	v_cvt_pk_bf16_f32 v61, v222, v223
	v_cvt_pk_bf16_f32 v62, v224, v225
	v_cvt_pk_bf16_f32 v63, v226, v227
	v_cvt_pk_bf16_f32 v64, v228, v229
	v_cvt_pk_bf16_f32 v65, v230, v231
	v_cvt_pk_bf16_f32 v66, v232, v233
	v_cvt_pk_bf16_f32 v67, v234, v235
	global_store_dwordx2 v2, v[58:59], s[20:21]
	global_store_dwordx2 v2, v[60:61], s[20:21] offset:512
	global_store_dwordx2 v3, v[62:63], s[20:21]
	global_store_dwordx2 v3, v[64:65], s[20:21] offset:512
	global_store_dwordx2 v4, v[66:67], s[20:21] offset:1024
.Lprep_skip_L0_3:
	s_mul_i32 s24, s23, 4
	s_add_i32 s22, s22, s24
	s_cmp_lt_u32 s22, 0x2000
	s_cbranch_scc1 .Lprep_loop_L0
.Lprep_done_L0:
.LBB0_1121:
	s_getreg_b32 s6, hwreg(HW_REG_XCC_ID, 0, 4)
	s_waitcnt vmcnt(0)
	s_barrier
	s_and_saveexec_b64 s[0:1], s[46:47]
	s_cbranch_execz .LBB0_1173
	s_add_i32 s7, 0, 0x20160
	v_mov_b32_e32 v0, s7
	s_waitcnt vmcnt(0) expcnt(0) lgkmcnt(0)
	ds_read_b32 v2, v0
	s_add_i32 s7, 0, 0x20164
	v_mov_b32_e32 v0, s7
	ds_read_b32 v0, v0
	s_and_b32 s51, s6, 15
	s_waitcnt lgkmcnt(1)
	v_cmp_ne_u32_e32 vcc, 0, v2
	s_cbranch_vccnz .LBB0_1137
	s_add_u32 s6, s66, 0x1200
	s_addc_u32 s7, s67, 0
	s_add_u32 s14, s66, 0x1400
	s_addc_u32 s15, s67, 0
	s_add_u32 s16, s66, 0x1500
	s_addc_u32 s17, s67, 0
	s_add_u32 s18, s66, 0x1600
	s_addc_u32 s19, s67, 0
	s_add_u32 s20, s66, 0x1700
	s_addc_u32 s21, s67, 0
	s_add_u32 s22, s66, 0x1800
	s_addc_u32 s23, s67, 0
	s_add_u32 s24, s66, 0x1900
	s_addc_u32 s25, s67, 0
	s_add_u32 s26, s66, 0x1a00
	s_addc_u32 s27, s67, 0
	s_add_u32 s28, s66, 0x1b00
	s_addc_u32 s29, s67, 0
	s_add_u32 s30, s66, 0x1c00
	s_addc_u32 s31, s67, 0
	s_add_u32 s34, s66, 0x1d00
	s_addc_u32 s35, s67, 0
	s_add_u32 s36, s66, 0x1e00
	s_addc_u32 s37, s67, 0
	s_add_u32 s38, s66, 0x1f00
	s_addc_u32 s39, s67, 0
	s_add_u32 s40, s66, 0x2000
	s_addc_u32 s41, s67, 0
	s_add_u32 s42, s66, 0x2100
	s_addc_u32 s43, s67, 0
	s_add_u32 s44, s66, 0x2200
	s_addc_u32 s45, s67, 0
	s_mul_i32 s72, s65, s74
	s_add_u32 s58, s66, 0x2300
	s_mul_i32 s72, s72, s64
	s_addc_u32 s59, s67, 0
	s_mov_b32 s73, 1
	v_mov_b32_e32 v16, 0
	s_branch .LBB0_1125

.LBB0_2728:
	s_barrier
	v_lshrrev_b32_e32 v0, 6, v194
	s_lshl_b32 s19, s64, 3
	v_readfirstlane_b32 s18, v0
	s_lshl_b32 s20, s2, 3
	s_add_i32 s18, s18, s20
	s_cmp_lt_u32 s18, 0x2000
	s_cbranch_scc0 .Lprep_done_L1
	s_add_u32 s0, s66, 0x8000
	s_addc_u32 s1, s67, 0
	s_add_u32 s8, s66, 0x5801000
	s_addc_u32 s9, s67, 0
	v_and_b32_e32 v0, 63, v194
	v_mov_b32_e32 v11, 0
	v_and_b32_e32 v1, 15, v0
	v_lshlrev_b32_e32 v2, 3, v0
	v_add_u32_e32 v3, 0x1800, v2
	v_cmp_lt_u32_e32 vcc, 31, v0
	v_mov_b32_e32 v20, 0x1700
	s_nop 1
	v_cndmask_b32_e32 v20, 0, v20, vcc
	v_add_u32_e32 v4, v2, v20
	v_and_b32_e32 v21, 4, v1
	v_cmp_ne_u32_e32 vcc, 0, v21
	v_mov_b32_e32 v22, 1.0
	v_mov_b32_e32 v5, -1.0
	v_cndmask_b32_e32 v5, v5, v22, vcc
	v_mov_b32_e32 v6, 0x358637bd
	v_cmp_gt_u32_e32 vcc, 8, v1
	s_nop 1
	v_cndmask_b32_e64 v7, 0, 1, vcc
	v_mov_b32_e32 v22, 0x80
	v_cndmask_b32_e32 v8, v22, v11, vcc
	v_cmp_lt_u32_e32 vcc, 31, v0
	s_nop 1
	v_cndmask_b32_e32 v9, 0, v8, vcc
	v_and_b32_e32 v10, 3, v1
	v_lshlrev_b32_e32 v10, 5, v10
	global_load_dwordx4 v[24:27], v11, s[66:67] offset:152
	v_lshlrev_b32_e32 v20, 4, v1
	v_mov_b32_e32 v21, 0
	s_waitcnt vmcnt(0)
	v_lshl_add_u64 v[24:25], v[24:25], 0, v[20:21]
	v_lshl_add_u64 v[26:27], v[26:27], 0, v[20:21]
	global_load_dwordx4 v[12:15], v[24:25], off offset:256
	global_load_dwordx4 v[16:19], v[26:27], off offset:256
.Lprep_loop_L1:
	s_mov_b32 s28, s18
	s_mul_i32 s21, s28, 0x3000
	s_add_u32 s10, s8, s21
	s_addc_u32 s11, s9, 0
	s_lshl_b32 s21, s28, 1
	s_and_b32 s21, s21, 0xfff
	s_lshr_b32 s26, s21, 6
	s_and_b32 s27, s21, 63
	s_sub_i32 s26, s26, s27
	s_lshl_b32 s26, s26, 7
	s_lshl_b32 s27, s27, 7
	v_add_u32_e32 v236, s27, v10
	v_mad_i32_i24 v236, v7, s26, v236
	v_add_u32_e32 v237, v236, v8
	v_add_u32_e32 v238, v236, v9
	global_load_dwordx4 v[68:71], v236, s[0:1]
	global_load_dwordx4 v[72:75], v236, s[0:1] offset:16
	global_load_dwordx4 v[76:79], v237, s[0:1]
	global_load_dwordx4 v[80:83], v237, s[0:1] offset:16
	global_load_dwordx4 v[84:87], v238, s[0:1]
	global_load_dwordx4 v[88:91], v238, s[0:1] offset:16
	global_load_dwordx2 v[28:29], v2, s[10:11]
	global_load_dwordx2 v[30:31], v2, s[10:11] offset:512
	global_load_dwordx2 v[32:33], v3, s[10:11]
	global_load_dwordx2 v[34:35], v3, s[10:11] offset:512
	global_load_dwordx2 v[36:37], v4, s[10:11] offset:1024
	s_mul_i32 s20, s19, 1
	s_add_i32 s20, s20, s18
	s_cmp_lt_u32 s20, 0x2000
	s_cselect_b32 s28, s20, s18
	s_mul_i32 s21, s28, 0x3000
	s_add_u32 s12, s8, s21
	s_addc_u32 s13, s9, 0
	s_lshl_b32 s21, s28, 1
	s_and_b32 s21, s21, 0xfff
	s_lshr_b32 s26, s21, 6
	s_and_b32 s27, s21, 63
	s_sub_i32 s26, s26, s27
	s_lshl_b32 s26, s26, 7
	s_lshl_b32 s27, s27, 7
	v_add_u32_e32 v236, s27, v10
	v_mad_i32_i24 v236, v7, s26, v236
	v_add_u32_e32 v237, v236, v8
	v_add_u32_e32 v238, v236, v9
	global_load_dwordx4 v[92:95], v236, s[0:1]
	global_load_dwordx4 v[96:99], v236, s[0:1] offset:16
	global_load_dwordx4 v[100:103], v237, s[0:1]
	global_load_dwordx4 v[104:107], v237, s[0:1] offset:16
	global_load_dwordx4 v[108:111], v238, s[0:1]
	global_load_dwordx4 v[112:115], v238, s[0:1] offset:16
	global_load_dwordx2 v[38:39], v2, s[12:13]
	global_load_dwordx2 v[40:41], v2, s[12:13] offset:512
	global_load_dwordx2 v[42:43], v3, s[12:13]
	global_load_dwordx2 v[44:45], v3, s[12:13] offset:512
	global_load_dwordx2 v[46:47], v4, s[12:13] offset:1024
	s_mul_i32 s20, s19, 2
	s_add_i32 s20, s20, s18
	s_cmp_lt_u32 s20, 0x2000
	s_cselect_b32 s28, s20, s18
	s_mul_i32 s21, s28, 0x3000
	s_add_u32 s14, s8, s21
	s_addc_u32 s15, s9, 0
	s_lshl_b32 s21, s28, 1
	s_and_b32 s21, s21, 0xfff
	s_lshr_b32 s26, s21, 6
	s_and_b32 s27, s21, 63
	s_sub_i32 s26, s26, s27
	s_lshl_b32 s26, s26, 7
	s_lshl_b32 s27, s27, 7
	v_add_u32_e32 v236, s27, v10
	v_mad_i32_i24 v236, v7, s26, v236
	v_add_u32_e32 v237, v236, v8
	v_add_u32_e32 v238, v236, v9
	global_load_dwordx4 v[116:119], v236, s[0:1]
	global_load_dwordx4 v[120:123], v236, s[0:1] offset:16
	global_load_dwordx4 v[124:127], v237, s[0:1]
	global_load_dwordx4 v[128:131], v237, s[0:1] offset:16
	global_load_dwordx4 v[132:135], v238, s[0:1]
	global_load_dwordx4 v[136:139], v238, s[0:1] offset:16
	global_load_dwordx2 v[48:49], v2, s[14:15]
	global_load_dwordx2 v[50:51], v2, s[14:15] offset:512
	global_load_dwordx2 v[52:53], v3, s[14:15]
	global_load_dwordx2 v[54:55], v3, s[14:15] offset:512
	global_load_dwordx2 v[56:57], v4, s[14:15] offset:1024
	s_mul_i32 s20, s19, 3
	s_add_i32 s20, s20, s18
	s_cmp_lt_u32 s20, 0x2000
	s_cselect_b32 s28, s20, s18
	s_mul_i32 s21, s28, 0x3000
	s_add_u32 s16, s8, s21
	s_addc_u32 s17, s9, 0
	s_lshl_b32 s21, s28, 1
	s_and_b32 s21, s21, 0xfff
	s_lshr_b32 s26, s21, 6
	s_and_b32 s27, s21, 63
	s_sub_i32 s26, s26, s27
	s_lshl_b32 s26, s26, 7
	s_lshl_b32 s27, s27, 7
	v_add_u32_e32 v236, s27, v10
	v_mad_i32_i24 v236, v7, s26, v236
	v_add_u32_e32 v237, v236, v8
	v_add_u32_e32 v238, v236, v9
	global_load_dwordx4 v[140:143], v236, s[0:1]
	global_load_dwordx4 v[144:147], v236, s[0:1] offset:16
	global_load_dwordx4 v[148:151], v237, s[0:1]
	global_load_dwordx4 v[152:155], v237, s[0:1] offset:16
	global_load_dwordx4 v[156:159], v238, s[0:1]
	global_load_dwordx4 v[160:163], v238, s[0:1] offset:16
	global_load_dwordx2 v[58:59], v2, s[16:17]
	global_load_dwordx2 v[60:61], v2, s[16:17] offset:512
	global_load_dwordx2 v[62:63], v3, s[16:17]
	global_load_dwordx2 v[64:65], v3, s[16:17] offset:512
	global_load_dwordx2 v[66:67], v4, s[16:17] offset:1024
	s_waitcnt vmcnt(33)
	v_mul_f32_e32 v69, v5, v69
	v_mul_f32_e32 v71, v5, v71
	v_mul_f32_e32 v73, v5, v73
	v_mul_f32_e32 v75, v5, v75
	v_mul_f32_e32 v77, v5, v77
	v_mul_f32_e32 v79, v5, v79
	v_mul_f32_e32 v81, v5, v81
	v_mul_f32_e32 v83, v5, v83
	v_mul_f32_e32 v85, v5, v85
	v_mul_f32_e32 v87, v5, v87
	v_mul_f32_e32 v89, v5, v89
	v_mul_f32_e32 v91, v5, v91
	v_lshlrev_b32_e32 v164, 16, v28
	v_and_b32_e32 v165, 0xffff0000, v28
	v_lshlrev_b32_e32 v166, 16, v29
	v_and_b32_e32 v167, 0xffff0000, v29
	v_lshlrev_b32_e32 v168, 16, v30
	v_and_b32_e32 v169, 0xffff0000, v30
	v_lshlrev_b32_e32 v170, 16, v31
	v_and_b32_e32 v171, 0xffff0000, v31
	v_lshlrev_b32_e32 v172, 16, v32
	v_and_b32_e32 v173, 0xffff0000, v32
	v_lshlrev_b32_e32 v174, 16, v33
	v_and_b32_e32 v175, 0xffff0000, v33
	v_lshlrev_b32_e32 v176, 16, v34
	v_and_b32_e32 v177, 0xffff0000, v34
	v_lshlrev_b32_e32 v178, 16, v35
	v_and_b32_e32 v179, 0xffff0000, v35
	v_lshlrev_b32_e32 v180, 16, v36
	v_and_b32_e32 v181, 0xffff0000, v36
	v_lshlrev_b32_e32 v182, 16, v37
	v_and_b32_e32 v183, 0xffff0000, v37
	v_mul_f32_e32 v184, v164, v164
	v_fmac_f32_e32 v184, v165, v165
	v_fmac_f32_e32 v184, v166, v166
	v_fmac_f32_e32 v184, v167, v167
	v_mul_f32_e32 v185, v168, v168
	v_fmac_f32_e32 v185, v169, v169
	v_fmac_f32_e32 v185, v170, v170
	v_fmac_f32_e32 v185, v171, v171
	v_mul_f32_e32 v186, v172, v172
	v_fmac_f32_e32 v186, v173, v173
	v_fmac_f32_e32 v186, v174, v174
	v_fmac_f32_e32 v186, v175, v175
	v_mul_f32_e32 v187, v176, v176
	v_fmac_f32_e32 v187, v177, v177
	v_fmac_f32_e32 v187, v178, v178
	v_fmac_f32_e32 v187, v179, v179
	v_mul_f32_e32 v188, v180, v180
	v_fmac_f32_e32 v188, v181, v181
	v_fmac_f32_e32 v188, v182, v182
	v_fmac_f32_e32 v188, v183, v183
	v_add_f32_dpp v184, v184, v184 quad_perm:[1,0,3,2] row_mask:0xf bank_mask:0xf
	v_add_f32_dpp v185, v185, v185 quad_perm:[1,0,3,2] row_mask:0xf bank_mask:0xf
	v_add_f32_dpp v186, v186, v186 quad_perm:[1,0,3,2] row_mask:0xf bank_mask:0xf
	v_add_f32_dpp v187, v187, v187 quad_perm:[1,0,3,2] row_mask:0xf bank_mask:0xf
	v_add_f32_dpp v188, v188, v188 quad_perm:[1,0,3,2] row_mask:0xf bank_mask:0xf
	v_add_f32_dpp v184, v184, v184 quad_perm:[2,3,0,1] row_mask:0xf bank_mask:0xf
	v_add_f32_dpp v185, v185, v185 quad_perm:[2,3,0,1] row_mask:0xf bank_mask:0xf
	v_add_f32_dpp v186, v186, v186 quad_perm:[2,3,0,1] row_mask:0xf bank_mask:0xf
	v_add_f32_dpp v187, v187, v187 quad_perm:[2,3,0,1] row_mask:0xf bank_mask:0xf
	v_add_f32_dpp v188, v188, v188 quad_perm:[2,3,0,1] row_mask:0xf bank_mask:0xf
	v_add_f32_dpp v184, v184, v184 row_half_mirror row_mask:0xf bank_mask:0xf
	v_add_f32_dpp v185, v185, v185 row_half_mirror row_mask:0xf bank_mask:0xf
	v_add_f32_dpp v186, v186, v186 row_half_mirror row_mask:0xf bank_mask:0xf
	v_add_f32_dpp v187, v187, v187 row_half_mirror row_mask:0xf bank_mask:0xf
	v_add_f32_dpp v188, v188, v188 row_half_mirror row_mask:0xf bank_mask:0xf
	v_add_f32_dpp v184, v184, v184 row_mirror row_mask:0xf bank_mask:0xf
	v_add_f32_dpp v185, v185, v185 row_mirror row_mask:0xf bank_mask:0xf
	v_add_f32_dpp v186, v186, v186 row_mirror row_mask:0xf bank_mask:0xf
	v_add_f32_dpp v187, v187, v187 row_mirror row_mask:0xf bank_mask:0xf
	v_add_f32_dpp v188, v188, v188 row_mirror row_mask:0xf bank_mask:0xf
	v_fmamk_f32 v184, v184, 0x3c800000, v6
	v_fmamk_f32 v185, v185, 0x3c800000, v6
	v_fmamk_f32 v186, v186, 0x3c800000, v6
	v_fmamk_f32 v187, v187, 0x3c800000, v6
	v_fmamk_f32 v188, v188, 0x3c800000, v6
	v_rsq_f32_e32 v184, v184
	v_rsq_f32_e32 v185, v185
	v_rsq_f32_e32 v186, v186
	v_rsq_f32_e32 v187, v187
	v_rsq_f32_e32 v188, v188
	v_mul_f32_e32 v164, v184, v164
	v_mul_f32_e32 v165, v184, v165
	v_mul_f32_e32 v166, v184, v166
	v_mul_f32_e32 v167, v184, v167
	v_mul_f32_e32 v168, v185, v168
	v_mul_f32_e32 v169, v185, v169
	v_mul_f32_e32 v170, v185, v170
	v_mul_f32_e32 v171, v185, v171
	v_mul_f32_e32 v172, v186, v172
	v_mul_f32_e32 v173, v186, v173
	v_mul_f32_e32 v174, v186, v174
	v_mul_f32_e32 v175, v186, v175
	v_mul_f32_e32 v176, v187, v176
	v_mul_f32_e32 v177, v187, v177
	v_mul_f32_e32 v178, v187, v178
	v_mul_f32_e32 v179, v187, v179
	v_mul_f32_e32 v180, v188, v180
	v_mul_f32_e32 v181, v188, v181
	v_mul_f32_e32 v182, v188, v182
	v_mul_f32_e32 v183, v188, v183
	v_mul_f32_e32 v164, v12, v164
	v_mul_f32_e32 v165, v13, v165
	v_mul_f32_e32 v166, v14, v166
	v_mul_f32_e32 v167, v15, v167
	v_mul_f32_e32 v168, v12, v168
	v_mul_f32_e32 v169, v13, v169
	v_mul_f32_e32 v170, v14, v170
	v_mul_f32_e32 v171, v15, v171
	v_mul_f32_e32 v172, v12, v172
	v_mul_f32_e32 v173, v13, v173
	v_mul_f32_e32 v174, v14, v174
	v_mul_f32_e32 v175, v15, v175
	v_mul_f32_e32 v176, v12, v176
	v_mul_f32_e32 v177, v13, v177
	v_mul_f32_e32 v178, v14, v178
	v_mul_f32_e32 v179, v15, v179
	v_mul_f32_e32 v180, v16, v180
	v_mul_f32_e32 v181, v17, v181
	v_mul_f32_e32 v182, v18, v182
	v_mul_f32_e32 v183, v19, v183
	v_mov_b32_dpp v196, v164 row_half_mirror row_mask:0xf bank_mask:0xf
	v_mov_b32_dpp v197, v165 row_half_mirror row_mask:0xf bank_mask:0xf
	v_mov_b32_dpp v198, v166 row_half_mirror row_mask:0xf bank_mask:0xf
	v_mov_b32_dpp v199, v167 row_half_mirror row_mask:0xf bank_mask:0xf
	v_mov_b32_dpp v200, v168 row_half_mirror row_mask:0xf bank_mask:0xf
	v_mov_b32_dpp v201, v169 row_half_mirror row_mask:0xf bank_mask:0xf
	v_mov_b32_dpp v202, v170 row_half_mirror row_mask:0xf bank_mask:0xf
	v_mov_b32_dpp v203, v171 row_half_mirror row_mask:0xf bank_mask:0xf
	v_mov_b32_dpp v204, v172 row_half_mirror row_mask:0xf bank_mask:0xf
	v_mov_b32_dpp v205, v173 row_half_mirror row_mask:0xf bank_mask:0xf
	v_mov_b32_dpp v206, v174 row_half_mirror row_mask:0xf bank_mask:0xf
	v_mov_b32_dpp v207, v175 row_half_mirror row_mask:0xf bank_mask:0xf
	v_mov_b32_dpp v208, v176 row_half_mirror row_mask:0xf bank_mask:0xf
	v_mov_b32_dpp v209, v177 row_half_mirror row_mask:0xf bank_mask:0xf
	v_mov_b32_dpp v210, v178 row_half_mirror row_mask:0xf bank_mask:0xf
	v_mov_b32_dpp v211, v179 row_half_mirror row_mask:0xf bank_mask:0xf
	v_mov_b32_dpp v212, v180 row_half_mirror row_mask:0xf bank_mask:0xf
	v_mov_b32_dpp v213, v181 row_half_mirror row_mask:0xf bank_mask:0xf
	v_mov_b32_dpp v214, v182 row_half_mirror row_mask:0xf bank_mask:0xf
	v_mov_b32_dpp v215, v183 row_half_mirror row_mask:0xf bank_mask:0xf
	v_mov_b32_dpp v216, v196 quad_perm:[3,2,1,0] row_mask:0xf bank_mask:0xf
	v_mov_b32_dpp v217, v197 quad_perm:[3,2,1,0] row_mask:0xf bank_mask:0xf
	v_mov_b32_dpp v218, v198 quad_perm:[3,2,1,0] row_mask:0xf bank_mask:0xf
	v_mov_b32_dpp v219, v199 quad_perm:[3,2,1,0] row_mask:0xf bank_mask:0xf
	v_mov_b32_dpp v220, v200 quad_perm:[3,2,1,0] row_mask:0xf bank_mask:0xf
	v_mov_b32_dpp v221, v201 quad_perm:[3,2,1,0] row_mask:0xf bank_mask:0xf
	v_mov_b32_dpp v222, v202 quad_perm:[3,2,1,0] row_mask:0xf bank_mask:0xf
	v_mov_b32_dpp v223, v203 quad_perm:[3,2,1,0] row_mask:0xf bank_mask:0xf
	v_mov_b32_dpp v224, v204 quad_perm:[3,2,1,0] row_mask:0xf bank_mask:0xf
	v_mov_b32_dpp v225, v205 quad_perm:[3,2,1,0] row_mask:0xf bank_mask:0xf
	v_mov_b32_dpp v226, v206 quad_perm:[3,2,1,0] row_mask:0xf bank_mask:0xf
	v_mov_b32_dpp v227, v207 quad_perm:[3,2,1,0] row_mask:0xf bank_mask:0xf
	v_mov_b32_dpp v228, v208 quad_perm:[3,2,1,0] row_mask:0xf bank_mask:0xf
	v_mov_b32_dpp v229, v209 quad_perm:[3,2,1,0] row_mask:0xf bank_mask:0xf
	v_mov_b32_dpp v230, v210 quad_perm:[3,2,1,0] row_mask:0xf bank_mask:0xf
	v_mov_b32_dpp v231, v211 quad_perm:[3,2,1,0] row_mask:0xf bank_mask:0xf
	v_mov_b32_dpp v232, v212 quad_perm:[3,2,1,0] row_mask:0xf bank_mask:0xf
	v_mov_b32_dpp v233, v213 quad_perm:[3,2,1,0] row_mask:0xf bank_mask:0xf
	v_mov_b32_dpp v234, v214 quad_perm:[3,2,1,0] row_mask:0xf bank_mask:0xf
	v_mov_b32_dpp v235, v215 quad_perm:[3,2,1,0] row_mask:0xf bank_mask:0xf
	v_mul_f32_e32 v216, v69, v216
	v_mul_f32_e32 v217, v71, v217
	v_mul_f32_e32 v218, v73, v218
	v_mul_f32_e32 v219, v75, v219
	v_mul_f32_e32 v220, v69, v220
	v_mul_f32_e32 v221, v71, v221
	v_mul_f32_e32 v222, v73, v222
	v_mul_f32_e32 v223, v75, v223
	v_mul_f32_e32 v224, v77, v224
	v_mul_f32_e32 v225, v79, v225
	v_mul_f32_e32 v226, v81, v226
	v_mul_f32_e32 v227, v83, v227
	v_mul_f32_e32 v228, v77, v228
	v_mul_f32_e32 v229, v79, v229
	v_mul_f32_e32 v230, v81, v230
	v_mul_f32_e32 v231, v83, v231
	v_mul_f32_e32 v232, v85, v232
	v_mul_f32_e32 v233, v87, v233
	v_mul_f32_e32 v234, v89, v234
	v_mul_f32_e32 v235, v91, v235
	v_fmac_f32_e32 v216, v68, v164
	v_fmac_f32_e32 v217, v70, v165
	v_fmac_f32_e32 v218, v72, v166
	v_fmac_f32_e32 v219, v74, v167
	v_fmac_f32_e32 v220, v68, v168
	v_fmac_f32_e32 v221, v70, v169
	v_fmac_f32_e32 v222, v72, v170
	v_fmac_f32_e32 v223, v74, v171
	v_fmac_f32_e32 v224, v76, v172
	v_fmac_f32_e32 v225, v78, v173
	v_fmac_f32_e32 v226, v80, v174
	v_fmac_f32_e32 v227, v82, v175
	v_fmac_f32_e32 v228, v76, v176
	v_fmac_f32_e32 v229, v78, v177
	v_fmac_f32_e32 v230, v80, v178
	v_fmac_f32_e32 v231, v82, v179
	v_fmac_f32_e32 v232, v84, v180
	v_fmac_f32_e32 v233, v86, v181
	v_fmac_f32_e32 v234, v88, v182
	v_fmac_f32_e32 v235, v90, v183
	v_mul_f32_e32 v216, 0x3e38aa3b, v216
	v_mul_f32_e32 v217, 0x3e38aa3b, v217
	v_mul_f32_e32 v218, 0x3e38aa3b, v218
	v_mul_f32_e32 v219, 0x3e38aa3b, v219
	v_mul_f32_e32 v220, 0x3e38aa3b, v220
	v_mul_f32_e32 v221, 0x3e38aa3b, v221
	v_mul_f32_e32 v222, 0x3e38aa3b, v222
	v_mul_f32_e32 v223, 0x3e38aa3b, v223
	v_mul_f32_e32 v224, 0x3e38aa3b, v224
	v_mul_f32_e32 v225, 0x3e38aa3b, v225
	v_mul_f32_e32 v226, 0x3e38aa3b, v226
	v_mul_f32_e32 v227, 0x3e38aa3b, v227
	v_mul_f32_e32 v228, 0x3e38aa3b, v228
	v_mul_f32_e32 v229, 0x3e38aa3b, v229
	v_mul_f32_e32 v230, 0x3e38aa3b, v230
	v_mul_f32_e32 v231, 0x3e38aa3b, v231
	v_cvt_pk_bf16_f32 v28, v216, v217
	v_cvt_pk_bf16_f32 v29, v218, v219
	v_cvt_pk_bf16_f32 v30, v220, v221
	v_cvt_pk_bf16_f32 v31, v222, v223
	v_cvt_pk_bf16_f32 v32, v224, v225
	v_cvt_pk_bf16_f32 v33, v226, v227
	v_cvt_pk_bf16_f32 v34, v228, v229
	v_cvt_pk_bf16_f32 v35, v230, v231
	v_cvt_pk_bf16_f32 v36, v232, v233
	v_cvt_pk_bf16_f32 v37, v234, v235
	global_store_dwordx2 v2, v[28:29], s[10:11]
	global_store_dwordx2 v2, v[30:31], s[10:11] offset:512
	global_store_dwordx2 v3, v[32:33], s[10:11]
	global_store_dwordx2 v3, v[34:35], s[10:11] offset:512
	global_store_dwordx2 v4, v[36:37], s[10:11] offset:1024
	s_mul_i32 s20, s19, 1
	s_add_i32 s20, s20, s18
	s_cmp_lt_u32 s20, 0x2000
	s_cbranch_scc0 .Lprep_skip_L1_1
	s_waitcnt vmcnt(27)
	v_mul_f32_e32 v93, v5, v93
	v_mul_f32_e32 v95, v5, v95
	v_mul_f32_e32 v97, v5, v97
	v_mul_f32_e32 v99, v5, v99
	v_mul_f32_e32 v101, v5, v101
	v_mul_f32_e32 v103, v5, v103
	v_mul_f32_e32 v105, v5, v105
	v_mul_f32_e32 v107, v5, v107
	v_mul_f32_e32 v109, v5, v109
	v_mul_f32_e32 v111, v5, v111
	v_mul_f32_e32 v113, v5, v113
	v_mul_f32_e32 v115, v5, v115
	v_lshlrev_b32_e32 v164, 16, v38
	v_and_b32_e32 v165, 0xffff0000, v38
	v_lshlrev_b32_e32 v166, 16, v39
	v_and_b32_e32 v167, 0xffff0000, v39
	v_lshlrev_b32_e32 v168, 16, v40
	v_and_b32_e32 v169, 0xffff0000, v40
	v_lshlrev_b32_e32 v170, 16, v41
	v_and_b32_e32 v171, 0xffff0000, v41
	v_lshlrev_b32_e32 v172, 16, v42
	v_and_b32_e32 v173, 0xffff0000, v42
	v_lshlrev_b32_e32 v174, 16, v43
	v_and_b32_e32 v175, 0xffff0000, v43
	v_lshlrev_b32_e32 v176, 16, v44
	v_and_b32_e32 v177, 0xffff0000, v44
	v_lshlrev_b32_e32 v178, 16, v45
	v_and_b32_e32 v179, 0xffff0000, v45
	v_lshlrev_b32_e32 v180, 16, v46
	v_and_b32_e32 v181, 0xffff0000, v46
	v_lshlrev_b32_e32 v182, 16, v47
	v_and_b32_e32 v183, 0xffff0000, v47
	v_mul_f32_e32 v184, v164, v164
	v_fmac_f32_e32 v184, v165, v165
	v_fmac_f32_e32 v184, v166, v166
	v_fmac_f32_e32 v184, v167, v167
	v_mul_f32_e32 v185, v168, v168
	v_fmac_f32_e32 v185, v169, v169
	v_fmac_f32_e32 v185, v170, v170
	v_fmac_f32_e32 v185, v171, v171
	v_mul_f32_e32 v186, v172, v172
	v_fmac_f32_e32 v186, v173, v173
	v_fmac_f32_e32 v186, v174, v174
	v_fmac_f32_e32 v186, v175, v175
	v_mul_f32_e32 v187, v176, v176
	v_fmac_f32_e32 v187, v177, v177
	v_fmac_f32_e32 v187, v178, v178
	v_fmac_f32_e32 v187, v179, v179
	v_mul_f32_e32 v188, v180, v180
	v_fmac_f32_e32 v188, v181, v181
	v_fmac_f32_e32 v188, v182, v182
	v_fmac_f32_e32 v188, v183, v183
	v_add_f32_dpp v184, v184, v184 quad_perm:[1,0,3,2] row_mask:0xf bank_mask:0xf
	v_add_f32_dpp v185, v185, v185 quad_perm:[1,0,3,2] row_mask:0xf bank_mask:0xf
	v_add_f32_dpp v186, v186, v186 quad_perm:[1,0,3,2] row_mask:0xf bank_mask:0xf
	v_add_f32_dpp v187, v187, v187 quad_perm:[1,0,3,2] row_mask:0xf bank_mask:0xf
	v_add_f32_dpp v188, v188, v188 quad_perm:[1,0,3,2] row_mask:0xf bank_mask:0xf
	v_add_f32_dpp v184, v184, v184 quad_perm:[2,3,0,1] row_mask:0xf bank_mask:0xf
	v_add_f32_dpp v185, v185, v185 quad_perm:[2,3,0,1] row_mask:0xf bank_mask:0xf
	v_add_f32_dpp v186, v186, v186 quad_perm:[2,3,0,1] row_mask:0xf bank_mask:0xf
	v_add_f32_dpp v187, v187, v187 quad_perm:[2,3,0,1] row_mask:0xf bank_mask:0xf
	v_add_f32_dpp v188, v188, v188 quad_perm:[2,3,0,1] row_mask:0xf bank_mask:0xf
	v_add_f32_dpp v184, v184, v184 row_half_mirror row_mask:0xf bank_mask:0xf
	v_add_f32_dpp v185, v185, v185 row_half_mirror row_mask:0xf bank_mask:0xf
	v_add_f32_dpp v186, v186, v186 row_half_mirror row_mask:0xf bank_mask:0xf
	v_add_f32_dpp v187, v187, v187 row_half_mirror row_mask:0xf bank_mask:0xf
	v_add_f32_dpp v188, v188, v188 row_half_mirror row_mask:0xf bank_mask:0xf
	v_add_f32_dpp v184, v184, v184 row_mirror row_mask:0xf bank_mask:0xf
	v_add_f32_dpp v185, v185, v185 row_mirror row_mask:0xf bank_mask:0xf
	v_add_f32_dpp v186, v186, v186 row_mirror row_mask:0xf bank_mask:0xf
	v_add_f32_dpp v187, v187, v187 row_mirror row_mask:0xf bank_mask:0xf
	v_add_f32_dpp v188, v188, v188 row_mirror row_mask:0xf bank_mask:0xf
	v_fmamk_f32 v184, v184, 0x3c800000, v6
	v_fmamk_f32 v185, v185, 0x3c800000, v6
	v_fmamk_f32 v186, v186, 0x3c800000, v6
	v_fmamk_f32 v187, v187, 0x3c800000, v6
	v_fmamk_f32 v188, v188, 0x3c800000, v6
	v_rsq_f32_e32 v184, v184
	v_rsq_f32_e32 v185, v185
	v_rsq_f32_e32 v186, v186
	v_rsq_f32_e32 v187, v187
	v_rsq_f32_e32 v188, v188
	v_mul_f32_e32 v164, v184, v164
	v_mul_f32_e32 v165, v184, v165
	v_mul_f32_e32 v166, v184, v166
	v_mul_f32_e32 v167, v184, v167
	v_mul_f32_e32 v168, v185, v168
	v_mul_f32_e32 v169, v185, v169
	v_mul_f32_e32 v170, v185, v170
	v_mul_f32_e32 v171, v185, v171
	v_mul_f32_e32 v172, v186, v172
	v_mul_f32_e32 v173, v186, v173
	v_mul_f32_e32 v174, v186, v174
	v_mul_f32_e32 v175, v186, v175
	v_mul_f32_e32 v176, v187, v176
	v_mul_f32_e32 v177, v187, v177
	v_mul_f32_e32 v178, v187, v178
	v_mul_f32_e32 v179, v187, v179
	v_mul_f32_e32 v180, v188, v180
	v_mul_f32_e32 v181, v188, v181
	v_mul_f32_e32 v182, v188, v182
	v_mul_f32_e32 v183, v188, v183
	v_mul_f32_e32 v164, v12, v164
	v_mul_f32_e32 v165, v13, v165
	v_mul_f32_e32 v166, v14, v166
	v_mul_f32_e32 v167, v15, v167
	v_mul_f32_e32 v168, v12, v168
	v_mul_f32_e32 v169, v13, v169
	v_mul_f32_e32 v170, v14, v170
	v_mul_f32_e32 v171, v15, v171
	v_mul_f32_e32 v172, v12, v172
	v_mul_f32_e32 v173, v13, v173
	v_mul_f32_e32 v174, v14, v174
	v_mul_f32_e32 v175, v15, v175
	v_mul_f32_e32 v176, v12, v176
	v_mul_f32_e32 v177, v13, v177
	v_mul_f32_e32 v178, v14, v178
	v_mul_f32_e32 v179, v15, v179
	v_mul_f32_e32 v180, v16, v180
	v_mul_f32_e32 v181, v17, v181
	v_mul_f32_e32 v182, v18, v182
	v_mul_f32_e32 v183, v19, v183
	v_mov_b32_dpp v196, v164 row_half_mirror row_mask:0xf bank_mask:0xf
	v_mov_b32_dpp v197, v165 row_half_mirror row_mask:0xf bank_mask:0xf
	v_mov_b32_dpp v198, v166 row_half_mirror row_mask:0xf bank_mask:0xf
	v_mov_b32_dpp v199, v167 row_half_mirror row_mask:0xf bank_mask:0xf
	v_mov_b32_dpp v200, v168 row_half_mirror row_mask:0xf bank_mask:0xf
	v_mov_b32_dpp v201, v169 row_half_mirror row_mask:0xf bank_mask:0xf
	v_mov_b32_dpp v202, v170 row_half_mirror row_mask:0xf bank_mask:0xf
	v_mov_b32_dpp v203, v171 row_half_mirror row_mask:0xf bank_mask:0xf
	v_mov_b32_dpp v204, v172 row_half_mirror row_mask:0xf bank_mask:0xf
	v_mov_b32_dpp v205, v173 row_half_mirror row_mask:0xf bank_mask:0xf
	v_mov_b32_dpp v206, v174 row_half_mirror row_mask:0xf bank_mask:0xf
	v_mov_b32_dpp v207, v175 row_half_mirror row_mask:0xf bank_mask:0xf
	v_mov_b32_dpp v208, v176 row_half_mirror row_mask:0xf bank_mask:0xf
	v_mov_b32_dpp v209, v177 row_half_mirror row_mask:0xf bank_mask:0xf
	v_mov_b32_dpp v210, v178 row_half_mirror row_mask:0xf bank_mask:0xf
	v_mov_b32_dpp v211, v179 row_half_mirror row_mask:0xf bank_mask:0xf
	v_mov_b32_dpp v212, v180 row_half_mirror row_mask:0xf bank_mask:0xf
	v_mov_b32_dpp v213, v181 row_half_mirror row_mask:0xf bank_mask:0xf
	v_mov_b32_dpp v214, v182 row_half_mirror row_mask:0xf bank_mask:0xf
	v_mov_b32_dpp v215, v183 row_half_mirror row_mask:0xf bank_mask:0xf
	v_mov_b32_dpp v216, v196 quad_perm:[3,2,1,0] row_mask:0xf bank_mask:0xf
	v_mov_b32_dpp v217, v197 quad_perm:[3,2,1,0] row_mask:0xf bank_mask:0xf
	v_mov_b32_dpp v218, v198 quad_perm:[3,2,1,0] row_mask:0xf bank_mask:0xf
	v_mov_b32_dpp v219, v199 quad_perm:[3,2,1,0] row_mask:0xf bank_mask:0xf
	v_mov_b32_dpp v220, v200 quad_perm:[3,2,1,0] row_mask:0xf bank_mask:0xf
	v_mov_b32_dpp v221, v201 quad_perm:[3,2,1,0] row_mask:0xf bank_mask:0xf
	v_mov_b32_dpp v222, v202 quad_perm:[3,2,1,0] row_mask:0xf bank_mask:0xf
	v_mov_b32_dpp v223, v203 quad_perm:[3,2,1,0] row_mask:0xf bank_mask:0xf
	v_mov_b32_dpp v224, v204 quad_perm:[3,2,1,0] row_mask:0xf bank_mask:0xf
	v_mov_b32_dpp v225, v205 quad_perm:[3,2,1,0] row_mask:0xf bank_mask:0xf
	v_mov_b32_dpp v226, v206 quad_perm:[3,2,1,0] row_mask:0xf bank_mask:0xf
	v_mov_b32_dpp v227, v207 quad_perm:[3,2,1,0] row_mask:0xf bank_mask:0xf
	v_mov_b32_dpp v228, v208 quad_perm:[3,2,1,0] row_mask:0xf bank_mask:0xf
	v_mov_b32_dpp v229, v209 quad_perm:[3,2,1,0] row_mask:0xf bank_mask:0xf
	v_mov_b32_dpp v230, v210 quad_perm:[3,2,1,0] row_mask:0xf bank_mask:0xf
	v_mov_b32_dpp v231, v211 quad_perm:[3,2,1,0] row_mask:0xf bank_mask:0xf
	v_mov_b32_dpp v232, v212 quad_perm:[3,2,1,0] row_mask:0xf bank_mask:0xf
	v_mov_b32_dpp v233, v213 quad_perm:[3,2,1,0] row_mask:0xf bank_mask:0xf
	v_mov_b32_dpp v234, v214 quad_perm:[3,2,1,0] row_mask:0xf bank_mask:0xf
	v_mov_b32_dpp v235, v215 quad_perm:[3,2,1,0] row_mask:0xf bank_mask:0xf
	v_mul_f32_e32 v216, v93, v216
	v_mul_f32_e32 v217, v95, v217
	v_mul_f32_e32 v218, v97, v218
	v_mul_f32_e32 v219, v99, v219
	v_mul_f32_e32 v220, v93, v220
	v_mul_f32_e32 v221, v95, v221
	v_mul_f32_e32 v222, v97, v222
	v_mul_f32_e32 v223, v99, v223
	v_mul_f32_e32 v224, v101, v224
	v_mul_f32_e32 v225, v103, v225
	v_mul_f32_e32 v226, v105, v226
	v_mul_f32_e32 v227, v107, v227
	v_mul_f32_e32 v228, v101, v228
	v_mul_f32_e32 v229, v103, v229
	v_mul_f32_e32 v230, v105, v230
	v_mul_f32_e32 v231, v107, v231
	v_mul_f32_e32 v232, v109, v232
	v_mul_f32_e32 v233, v111, v233
	v_mul_f32_e32 v234, v113, v234
	v_mul_f32_e32 v235, v115, v235
	v_fmac_f32_e32 v216, v92, v164
	v_fmac_f32_e32 v217, v94, v165
	v_fmac_f32_e32 v218, v96, v166
	v_fmac_f32_e32 v219, v98, v167
	v_fmac_f32_e32 v220, v92, v168
	v_fmac_f32_e32 v221, v94, v169
	v_fmac_f32_e32 v222, v96, v170
	v_fmac_f32_e32 v223, v98, v171
	v_fmac_f32_e32 v224, v100, v172
	v_fmac_f32_e32 v225, v102, v173
	v_fmac_f32_e32 v226, v104, v174
	v_fmac_f32_e32 v227, v106, v175
	v_fmac_f32_e32 v228, v100, v176
	v_fmac_f32_e32 v229, v102, v177
	v_fmac_f32_e32 v230, v104, v178
	v_fmac_f32_e32 v231, v106, v179
	v_fmac_f32_e32 v232, v108, v180
	v_fmac_f32_e32 v233, v110, v181
	v_fmac_f32_e32 v234, v112, v182
	v_fmac_f32_e32 v235, v114, v183
	v_mul_f32_e32 v216, 0x3e38aa3b, v216
	v_mul_f32_e32 v217, 0x3e38aa3b, v217
	v_mul_f32_e32 v218, 0x3e38aa3b, v218
	v_mul_f32_e32 v219, 0x3e38aa3b, v219
	v_mul_f32_e32 v220, 0x3e38aa3b, v220
	v_mul_f32_e32 v221, 0x3e38aa3b, v221
	v_mul_f32_e32 v222, 0x3e38aa3b, v222
	v_mul_f32_e32 v223, 0x3e38aa3b, v223
	v_mul_f32_e32 v224, 0x3e38aa3b, v224
	v_mul_f32_e32 v225, 0x3e38aa3b, v225
	v_mul_f32_e32 v226, 0x3e38aa3b, v226
	v_mul_f32_e32 v227, 0x3e38aa3b, v227
	v_mul_f32_e32 v228, 0x3e38aa3b, v228
	v_mul_f32_e32 v229, 0x3e38aa3b, v229
	v_mul_f32_e32 v230, 0x3e38aa3b, v230
	v_mul_f32_e32 v231, 0x3e38aa3b, v231
	v_cvt_pk_bf16_f32 v38, v216, v217
	v_cvt_pk_bf16_f32 v39, v218, v219
	v_cvt_pk_bf16_f32 v40, v220, v221
	v_cvt_pk_bf16_f32 v41, v222, v223
	v_cvt_pk_bf16_f32 v42, v224, v225
	v_cvt_pk_bf16_f32 v43, v226, v227
	v_cvt_pk_bf16_f32 v44, v228, v229
	v_cvt_pk_bf16_f32 v45, v230, v231
	v_cvt_pk_bf16_f32 v46, v232, v233
	v_cvt_pk_bf16_f32 v47, v234, v235
	global_store_dwordx2 v2, v[38:39], s[12:13]
	global_store_dwordx2 v2, v[40:41], s[12:13] offset:512
	global_store_dwordx2 v3, v[42:43], s[12:13]
	global_store_dwordx2 v3, v[44:45], s[12:13] offset:512
	global_store_dwordx2 v4, v[46:47], s[12:13] offset:1024
.Lprep_skip_L1_1:
	s_mul_i32 s20, s19, 2
	s_add_i32 s20, s20, s18
	s_cmp_lt_u32 s20, 0x2000
	s_cbranch_scc0 .Lprep_skip_L1_2
	s_waitcnt vmcnt(21)
	v_mul_f32_e32 v117, v5, v117
	v_mul_f32_e32 v119, v5, v119
	v_mul_f32_e32 v121, v5, v121
	v_mul_f32_e32 v123, v5, v123
	v_mul_f32_e32 v125, v5, v125
	v_mul_f32_e32 v127, v5, v127
	v_mul_f32_e32 v129, v5, v129
	v_mul_f32_e32 v131, v5, v131
	v_mul_f32_e32 v133, v5, v133
	v_mul_f32_e32 v135, v5, v135
	v_mul_f32_e32 v137, v5, v137
	v_mul_f32_e32 v139, v5, v139
	v_lshlrev_b32_e32 v164, 16, v48
	v_and_b32_e32 v165, 0xffff0000, v48
	v_lshlrev_b32_e32 v166, 16, v49
	v_and_b32_e32 v167, 0xffff0000, v49
	v_lshlrev_b32_e32 v168, 16, v50
	v_and_b32_e32 v169, 0xffff0000, v50
	v_lshlrev_b32_e32 v170, 16, v51
	v_and_b32_e32 v171, 0xffff0000, v51
	v_lshlrev_b32_e32 v172, 16, v52
	v_and_b32_e32 v173, 0xffff0000, v52
	v_lshlrev_b32_e32 v174, 16, v53
	v_and_b32_e32 v175, 0xffff0000, v53
	v_lshlrev_b32_e32 v176, 16, v54
	v_and_b32_e32 v177, 0xffff0000, v54
	v_lshlrev_b32_e32 v178, 16, v55
	v_and_b32_e32 v179, 0xffff0000, v55
	v_lshlrev_b32_e32 v180, 16, v56
	v_and_b32_e32 v181, 0xffff0000, v56
	v_lshlrev_b32_e32 v182, 16, v57
	v_and_b32_e32 v183, 0xffff0000, v57
	v_mul_f32_e32 v184, v164, v164
	v_fmac_f32_e32 v184, v165, v165
	v_fmac_f32_e32 v184, v166, v166
	v_fmac_f32_e32 v184, v167, v167
	v_mul_f32_e32 v185, v168, v168
	v_fmac_f32_e32 v185, v169, v169
	v_fmac_f32_e32 v185, v170, v170
	v_fmac_f32_e32 v185, v171, v171
	v_mul_f32_e32 v186, v172, v172
	v_fmac_f32_e32 v186, v173, v173
	v_fmac_f32_e32 v186, v174, v174
	v_fmac_f32_e32 v186, v175, v175
	v_mul_f32_e32 v187, v176, v176
	v_fmac_f32_e32 v187, v177, v177
	v_fmac_f32_e32 v187, v178, v178
	v_fmac_f32_e32 v187, v179, v179
	v_mul_f32_e32 v188, v180, v180
	v_fmac_f32_e32 v188, v181, v181
	v_fmac_f32_e32 v188, v182, v182
	v_fmac_f32_e32 v188, v183, v183
	v_add_f32_dpp v184, v184, v184 quad_perm:[1,0,3,2] row_mask:0xf bank_mask:0xf
	v_add_f32_dpp v185, v185, v185 quad_perm:[1,0,3,2] row_mask:0xf bank_mask:0xf
	v_add_f32_dpp v186, v186, v186 quad_perm:[1,0,3,2] row_mask:0xf bank_mask:0xf
	v_add_f32_dpp v187, v187, v187 quad_perm:[1,0,3,2] row_mask:0xf bank_mask:0xf
	v_add_f32_dpp v188, v188, v188 quad_perm:[1,0,3,2] row_mask:0xf bank_mask:0xf
	v_add_f32_dpp v184, v184, v184 quad_perm:[2,3,0,1] row_mask:0xf bank_mask:0xf
	v_add_f32_dpp v185, v185, v185 quad_perm:[2,3,0,1] row_mask:0xf bank_mask:0xf
	v_add_f32_dpp v186, v186, v186 quad_perm:[2,3,0,1] row_mask:0xf bank_mask:0xf
	v_add_f32_dpp v187, v187, v187 quad_perm:[2,3,0,1] row_mask:0xf bank_mask:0xf
	v_add_f32_dpp v188, v188, v188 quad_perm:[2,3,0,1] row_mask:0xf bank_mask:0xf
	v_add_f32_dpp v184, v184, v184 row_half_mirror row_mask:0xf bank_mask:0xf
	v_add_f32_dpp v185, v185, v185 row_half_mirror row_mask:0xf bank_mask:0xf
	v_add_f32_dpp v186, v186, v186 row_half_mirror row_mask:0xf bank_mask:0xf
	v_add_f32_dpp v187, v187, v187 row_half_mirror row_mask:0xf bank_mask:0xf
	v_add_f32_dpp v188, v188, v188 row_half_mirror row_mask:0xf bank_mask:0xf
	v_add_f32_dpp v184, v184, v184 row_mirror row_mask:0xf bank_mask:0xf
	v_add_f32_dpp v185, v185, v185 row_mirror row_mask:0xf bank_mask:0xf
	v_add_f32_dpp v186, v186, v186 row_mirror row_mask:0xf bank_mask:0xf
	v_add_f32_dpp v187, v187, v187 row_mirror row_mask:0xf bank_mask:0xf
	v_add_f32_dpp v188, v188, v188 row_mirror row_mask:0xf bank_mask:0xf
	v_fmamk_f32 v184, v184, 0x3c800000, v6
	v_fmamk_f32 v185, v185, 0x3c800000, v6
	v_fmamk_f32 v186, v186, 0x3c800000, v6
	v_fmamk_f32 v187, v187, 0x3c800000, v6
	v_fmamk_f32 v188, v188, 0x3c800000, v6
	v_rsq_f32_e32 v184, v184
	v_rsq_f32_e32 v185, v185
	v_rsq_f32_e32 v186, v186
	v_rsq_f32_e32 v187, v187
	v_rsq_f32_e32 v188, v188
	v_mul_f32_e32 v164, v184, v164
	v_mul_f32_e32 v165, v184, v165
	v_mul_f32_e32 v166, v184, v166
	v_mul_f32_e32 v167, v184, v167
	v_mul_f32_e32 v168, v185, v168
	v_mul_f32_e32 v169, v185, v169
	v_mul_f32_e32 v170, v185, v170
	v_mul_f32_e32 v171, v185, v171
	v_mul_f32_e32 v172, v186, v172
	v_mul_f32_e32 v173, v186, v173
	v_mul_f32_e32 v174, v186, v174
	v_mul_f32_e32 v175, v186, v175
	v_mul_f32_e32 v176, v187, v176
	v_mul_f32_e32 v177, v187, v177
	v_mul_f32_e32 v178, v187, v178
	v_mul_f32_e32 v179, v187, v179
	v_mul_f32_e32 v180, v188, v180
	v_mul_f32_e32 v181, v188, v181
	v_mul_f32_e32 v182, v188, v182
	v_mul_f32_e32 v183, v188, v183
	v_mul_f32_e32 v164, v12, v164
	v_mul_f32_e32 v165, v13, v165
	v_mul_f32_e32 v166, v14, v166
	v_mul_f32_e32 v167, v15, v167
	v_mul_f32_e32 v168, v12, v168
	v_mul_f32_e32 v169, v13, v169
	v_mul_f32_e32 v170, v14, v170
	v_mul_f32_e32 v171, v15, v171
	v_mul_f32_e32 v172, v12, v172
	v_mul_f32_e32 v173, v13, v173
	v_mul_f32_e32 v174, v14, v174
	v_mul_f32_e32 v175, v15, v175
	v_mul_f32_e32 v176, v12, v176
	v_mul_f32_e32 v177, v13, v177
	v_mul_f32_e32 v178, v14, v178
	v_mul_f32_e32 v179, v15, v179
	v_mul_f32_e32 v180, v16, v180
	v_mul_f32_e32 v181, v17, v181
	v_mul_f32_e32 v182, v18, v182
	v_mul_f32_e32 v183, v19, v183
	v_mov_b32_dpp v196, v164 row_half_mirror row_mask:0xf bank_mask:0xf
	v_mov_b32_dpp v197, v165 row_half_mirror row_mask:0xf bank_mask:0xf
	v_mov_b32_dpp v198, v166 row_half_mirror row_mask:0xf bank_mask:0xf
	v_mov_b32_dpp v199, v167 row_half_mirror row_mask:0xf bank_mask:0xf
	v_mov_b32_dpp v200, v168 row_half_mirror row_mask:0xf bank_mask:0xf
	v_mov_b32_dpp v201, v169 row_half_mirror row_mask:0xf bank_mask:0xf
	v_mov_b32_dpp v202, v170 row_half_mirror row_mask:0xf bank_mask:0xf
	v_mov_b32_dpp v203, v171 row_half_mirror row_mask:0xf bank_mask:0xf
	v_mov_b32_dpp v204, v172 row_half_mirror row_mask:0xf bank_mask:0xf
	v_mov_b32_dpp v205, v173 row_half_mirror row_mask:0xf bank_mask:0xf
	v_mov_b32_dpp v206, v174 row_half_mirror row_mask:0xf bank_mask:0xf
	v_mov_b32_dpp v207, v175 row_half_mirror row_mask:0xf bank_mask:0xf
	v_mov_b32_dpp v208, v176 row_half_mirror row_mask:0xf bank_mask:0xf
	v_mov_b32_dpp v209, v177 row_half_mirror row_mask:0xf bank_mask:0xf
	v_mov_b32_dpp v210, v178 row_half_mirror row_mask:0xf bank_mask:0xf
	v_mov_b32_dpp v211, v179 row_half_mirror row_mask:0xf bank_mask:0xf
	v_mov_b32_dpp v212, v180 row_half_mirror row_mask:0xf bank_mask:0xf
	v_mov_b32_dpp v213, v181 row_half_mirror row_mask:0xf bank_mask:0xf
	v_mov_b32_dpp v214, v182 row_half_mirror row_mask:0xf bank_mask:0xf
	v_mov_b32_dpp v215, v183 row_half_mirror row_mask:0xf bank_mask:0xf
	v_mov_b32_dpp v216, v196 quad_perm:[3,2,1,0] row_mask:0xf bank_mask:0xf
	v_mov_b32_dpp v217, v197 quad_perm:[3,2,1,0] row_mask:0xf bank_mask:0xf
	v_mov_b32_dpp v218, v198 quad_perm:[3,2,1,0] row_mask:0xf bank_mask:0xf
	v_mov_b32_dpp v219, v199 quad_perm:[3,2,1,0] row_mask:0xf bank_mask:0xf
	v_mov_b32_dpp v220, v200 quad_perm:[3,2,1,0] row_mask:0xf bank_mask:0xf
	v_mov_b32_dpp v221, v201 quad_perm:[3,2,1,0] row_mask:0xf bank_mask:0xf
	v_mov_b32_dpp v222, v202 quad_perm:[3,2,1,0] row_mask:0xf bank_mask:0xf
	v_mov_b32_dpp v223, v203 quad_perm:[3,2,1,0] row_mask:0xf bank_mask:0xf
	v_mov_b32_dpp v224, v204 quad_perm:[3,2,1,0] row_mask:0xf bank_mask:0xf
	v_mov_b32_dpp v225, v205 quad_perm:[3,2,1,0] row_mask:0xf bank_mask:0xf
	v_mov_b32_dpp v226, v206 quad_perm:[3,2,1,0] row_mask:0xf bank_mask:0xf
	v_mov_b32_dpp v227, v207 quad_perm:[3,2,1,0] row_mask:0xf bank_mask:0xf
	v_mov_b32_dpp v228, v208 quad_perm:[3,2,1,0] row_mask:0xf bank_mask:0xf
	v_mov_b32_dpp v229, v209 quad_perm:[3,2,1,0] row_mask:0xf bank_mask:0xf
	v_mov_b32_dpp v230, v210 quad_perm:[3,2,1,0] row_mask:0xf bank_mask:0xf
	v_mov_b32_dpp v231, v211 quad_perm:[3,2,1,0] row_mask:0xf bank_mask:0xf
	v_mov_b32_dpp v232, v212 quad_perm:[3,2,1,0] row_mask:0xf bank_mask:0xf
	v_mov_b32_dpp v233, v213 quad_perm:[3,2,1,0] row_mask:0xf bank_mask:0xf
	v_mov_b32_dpp v234, v214 quad_perm:[3,2,1,0] row_mask:0xf bank_mask:0xf
	v_mov_b32_dpp v235, v215 quad_perm:[3,2,1,0] row_mask:0xf bank_mask:0xf
	v_mul_f32_e32 v216, v117, v216
	v_mul_f32_e32 v217, v119, v217
	v_mul_f32_e32 v218, v121, v218
	v_mul_f32_e32 v219, v123, v219
	v_mul_f32_e32 v220, v117, v220
	v_mul_f32_e32 v221, v119, v221
	v_mul_f32_e32 v222, v121, v222
	v_mul_f32_e32 v223, v123, v223
	v_mul_f32_e32 v224, v125, v224
	v_mul_f32_e32 v225, v127, v225
	v_mul_f32_e32 v226, v129, v226
	v_mul_f32_e32 v227, v131, v227
	v_mul_f32_e32 v228, v125, v228
	v_mul_f32_e32 v229, v127, v229
	v_mul_f32_e32 v230, v129, v230
	v_mul_f32_e32 v231, v131, v231
	v_mul_f32_e32 v232, v133, v232
	v_mul_f32_e32 v233, v135, v233
	v_mul_f32_e32 v234, v137, v234
	v_mul_f32_e32 v235, v139, v235
	v_fmac_f32_e32 v216, v116, v164
	v_fmac_f32_e32 v217, v118, v165
	v_fmac_f32_e32 v218, v120, v166
	v_fmac_f32_e32 v219, v122, v167
	v_fmac_f32_e32 v220, v116, v168
	v_fmac_f32_e32 v221, v118, v169
	v_fmac_f32_e32 v222, v120, v170
	v_fmac_f32_e32 v223, v122, v171
	v_fmac_f32_e32 v224, v124, v172
	v_fmac_f32_e32 v225, v126, v173
	v_fmac_f32_e32 v226, v128, v174
	v_fmac_f32_e32 v227, v130, v175
	v_fmac_f32_e32 v228, v124, v176
	v_fmac_f32_e32 v229, v126, v177
	v_fmac_f32_e32 v230, v128, v178
	v_fmac_f32_e32 v231, v130, v179
	v_fmac_f32_e32 v232, v132, v180
	v_fmac_f32_e32 v233, v134, v181
	v_fmac_f32_e32 v234, v136, v182
	v_fmac_f32_e32 v235, v138, v183
	v_mul_f32_e32 v216, 0x3e38aa3b, v216
	v_mul_f32_e32 v217, 0x3e38aa3b, v217
	v_mul_f32_e32 v218, 0x3e38aa3b, v218
	v_mul_f32_e32 v219, 0x3e38aa3b, v219
	v_mul_f32_e32 v220, 0x3e38aa3b, v220
	v_mul_f32_e32 v221, 0x3e38aa3b, v221
	v_mul_f32_e32 v222, 0x3e38aa3b, v222
	v_mul_f32_e32 v223, 0x3e38aa3b, v223
	v_mul_f32_e32 v224, 0x3e38aa3b, v224
	v_mul_f32_e32 v225, 0x3e38aa3b, v225
	v_mul_f32_e32 v226, 0x3e38aa3b, v226
	v_mul_f32_e32 v227, 0x3e38aa3b, v227
	v_mul_f32_e32 v228, 0x3e38aa3b, v228
	v_mul_f32_e32 v229, 0x3e38aa3b, v229
	v_mul_f32_e32 v230, 0x3e38aa3b, v230
	v_mul_f32_e32 v231, 0x3e38aa3b, v231
	v_cvt_pk_bf16_f32 v48, v216, v217
	v_cvt_pk_bf16_f32 v49, v218, v219
	v_cvt_pk_bf16_f32 v50, v220, v221
	v_cvt_pk_bf16_f32 v51, v222, v223
	v_cvt_pk_bf16_f32 v52, v224, v225
	v_cvt_pk_bf16_f32 v53, v226, v227
	v_cvt_pk_bf16_f32 v54, v228, v229
	v_cvt_pk_bf16_f32 v55, v230, v231
	v_cvt_pk_bf16_f32 v56, v232, v233
	v_cvt_pk_bf16_f32 v57, v234, v235
	global_store_dwordx2 v2, v[48:49], s[14:15]
	global_store_dwordx2 v2, v[50:51], s[14:15] offset:512
	global_store_dwordx2 v3, v[52:53], s[14:15]
	global_store_dwordx2 v3, v[54:55], s[14:15] offset:512
	global_store_dwordx2 v4, v[56:57], s[14:15] offset:1024
.Lprep_skip_L1_2:
	s_mul_i32 s20, s19, 3
	s_add_i32 s20, s20, s18
	s_cmp_lt_u32 s20, 0x2000
	s_cbranch_scc0 .Lprep_skip_L1_3
	s_waitcnt vmcnt(15)
	v_mul_f32_e32 v141, v5, v141
	v_mul_f32_e32 v143, v5, v143
	v_mul_f32_e32 v145, v5, v145
	v_mul_f32_e32 v147, v5, v147
	v_mul_f32_e32 v149, v5, v149
	v_mul_f32_e32 v151, v5, v151
	v_mul_f32_e32 v153, v5, v153
	v_mul_f32_e32 v155, v5, v155
	v_mul_f32_e32 v157, v5, v157
	v_mul_f32_e32 v159, v5, v159
	v_mul_f32_e32 v161, v5, v161
	v_mul_f32_e32 v163, v5, v163
	v_lshlrev_b32_e32 v164, 16, v58
	v_and_b32_e32 v165, 0xffff0000, v58
	v_lshlrev_b32_e32 v166, 16, v59
	v_and_b32_e32 v167, 0xffff0000, v59
	v_lshlrev_b32_e32 v168, 16, v60
	v_and_b32_e32 v169, 0xffff0000, v60
	v_lshlrev_b32_e32 v170, 16, v61
	v_and_b32_e32 v171, 0xffff0000, v61
	v_lshlrev_b32_e32 v172, 16, v62
	v_and_b32_e32 v173, 0xffff0000, v62
	v_lshlrev_b32_e32 v174, 16, v63
	v_and_b32_e32 v175, 0xffff0000, v63
	v_lshlrev_b32_e32 v176, 16, v64
	v_and_b32_e32 v177, 0xffff0000, v64
	v_lshlrev_b32_e32 v178, 16, v65
	v_and_b32_e32 v179, 0xffff0000, v65
	v_lshlrev_b32_e32 v180, 16, v66
	v_and_b32_e32 v181, 0xffff0000, v66
	v_lshlrev_b32_e32 v182, 16, v67
	v_and_b32_e32 v183, 0xffff0000, v67
	v_mul_f32_e32 v184, v164, v164
	v_fmac_f32_e32 v184, v165, v165
	v_fmac_f32_e32 v184, v166, v166
	v_fmac_f32_e32 v184, v167, v167
	v_mul_f32_e32 v185, v168, v168
	v_fmac_f32_e32 v185, v169, v169
	v_fmac_f32_e32 v185, v170, v170
	v_fmac_f32_e32 v185, v171, v171
	v_mul_f32_e32 v186, v172, v172
	v_fmac_f32_e32 v186, v173, v173
	v_fmac_f32_e32 v186, v174, v174
	v_fmac_f32_e32 v186, v175, v175
	v_mul_f32_e32 v187, v176, v176
	v_fmac_f32_e32 v187, v177, v177
	v_fmac_f32_e32 v187, v178, v178
	v_fmac_f32_e32 v187, v179, v179
	v_mul_f32_e32 v188, v180, v180
	v_fmac_f32_e32 v188, v181, v181
	v_fmac_f32_e32 v188, v182, v182
	v_fmac_f32_e32 v188, v183, v183
	v_add_f32_dpp v184, v184, v184 quad_perm:[1,0,3,2] row_mask:0xf bank_mask:0xf
	v_add_f32_dpp v185, v185, v185 quad_perm:[1,0,3,2] row_mask:0xf bank_mask:0xf
	v_add_f32_dpp v186, v186, v186 quad_perm:[1,0,3,2] row_mask:0xf bank_mask:0xf
	v_add_f32_dpp v187, v187, v187 quad_perm:[1,0,3,2] row_mask:0xf bank_mask:0xf
	v_add_f32_dpp v188, v188, v188 quad_perm:[1,0,3,2] row_mask:0xf bank_mask:0xf
	v_add_f32_dpp v184, v184, v184 quad_perm:[2,3,0,1] row_mask:0xf bank_mask:0xf
	v_add_f32_dpp v185, v185, v185 quad_perm:[2,3,0,1] row_mask:0xf bank_mask:0xf
	v_add_f32_dpp v186, v186, v186 quad_perm:[2,3,0,1] row_mask:0xf bank_mask:0xf
	v_add_f32_dpp v187, v187, v187 quad_perm:[2,3,0,1] row_mask:0xf bank_mask:0xf
	v_add_f32_dpp v188, v188, v188 quad_perm:[2,3,0,1] row_mask:0xf bank_mask:0xf
	v_add_f32_dpp v184, v184, v184 row_half_mirror row_mask:0xf bank_mask:0xf
	v_add_f32_dpp v185, v185, v185 row_half_mirror row_mask:0xf bank_mask:0xf
	v_add_f32_dpp v186, v186, v186 row_half_mirror row_mask:0xf bank_mask:0xf
	v_add_f32_dpp v187, v187, v187 row_half_mirror row_mask:0xf bank_mask:0xf
	v_add_f32_dpp v188, v188, v188 row_half_mirror row_mask:0xf bank_mask:0xf
	v_add_f32_dpp v184, v184, v184 row_mirror row_mask:0xf bank_mask:0xf
	v_add_f32_dpp v185, v185, v185 row_mirror row_mask:0xf bank_mask:0xf
	v_add_f32_dpp v186, v186, v186 row_mirror row_mask:0xf bank_mask:0xf
	v_add_f32_dpp v187, v187, v187 row_mirror row_mask:0xf bank_mask:0xf
	v_add_f32_dpp v188, v188, v188 row_mirror row_mask:0xf bank_mask:0xf
	v_fmamk_f32 v184, v184, 0x3c800000, v6
	v_fmamk_f32 v185, v185, 0x3c800000, v6
	v_fmamk_f32 v186, v186, 0x3c800000, v6
	v_fmamk_f32 v187, v187, 0x3c800000, v6
	v_fmamk_f32 v188, v188, 0x3c800000, v6
	v_rsq_f32_e32 v184, v184
	v_rsq_f32_e32 v185, v185
	v_rsq_f32_e32 v186, v186
	v_rsq_f32_e32 v187, v187
	v_rsq_f32_e32 v188, v188
	v_mul_f32_e32 v164, v184, v164
	v_mul_f32_e32 v165, v184, v165
	v_mul_f32_e32 v166, v184, v166
	v_mul_f32_e32 v167, v184, v167
	v_mul_f32_e32 v168, v185, v168
	v_mul_f32_e32 v169, v185, v169
	v_mul_f32_e32 v170, v185, v170
	v_mul_f32_e32 v171, v185, v171
	v_mul_f32_e32 v172, v186, v172
	v_mul_f32_e32 v173, v186, v173
	v_mul_f32_e32 v174, v186, v174
	v_mul_f32_e32 v175, v186, v175
	v_mul_f32_e32 v176, v187, v176
	v_mul_f32_e32 v177, v187, v177
	v_mul_f32_e32 v178, v187, v178
	v_mul_f32_e32 v179, v187, v179
	v_mul_f32_e32 v180, v188, v180
	v_mul_f32_e32 v181, v188, v181
	v_mul_f32_e32 v182, v188, v182
	v_mul_f32_e32 v183, v188, v183
	v_mul_f32_e32 v164, v12, v164
	v_mul_f32_e32 v165, v13, v165
	v_mul_f32_e32 v166, v14, v166
	v_mul_f32_e32 v167, v15, v167
	v_mul_f32_e32 v168, v12, v168
	v_mul_f32_e32 v169, v13, v169
	v_mul_f32_e32 v170, v14, v170
	v_mul_f32_e32 v171, v15, v171
	v_mul_f32_e32 v172, v12, v172
	v_mul_f32_e32 v173, v13, v173
	v_mul_f32_e32 v174, v14, v174
	v_mul_f32_e32 v175, v15, v175
	v_mul_f32_e32 v176, v12, v176
	v_mul_f32_e32 v177, v13, v177
	v_mul_f32_e32 v178, v14, v178
	v_mul_f32_e32 v179, v15, v179
	v_mul_f32_e32 v180, v16, v180
	v_mul_f32_e32 v181, v17, v181
	v_mul_f32_e32 v182, v18, v182
	v_mul_f32_e32 v183, v19, v183
	v_mov_b32_dpp v196, v164 row_half_mirror row_mask:0xf bank_mask:0xf
	v_mov_b32_dpp v197, v165 row_half_mirror row_mask:0xf bank_mask:0xf
	v_mov_b32_dpp v198, v166 row_half_mirror row_mask:0xf bank_mask:0xf
	v_mov_b32_dpp v199, v167 row_half_mirror row_mask:0xf bank_mask:0xf
	v_mov_b32_dpp v200, v168 row_half_mirror row_mask:0xf bank_mask:0xf
	v_mov_b32_dpp v201, v169 row_half_mirror row_mask:0xf bank_mask:0xf
	v_mov_b32_dpp v202, v170 row_half_mirror row_mask:0xf bank_mask:0xf
	v_mov_b32_dpp v203, v171 row_half_mirror row_mask:0xf bank_mask:0xf
	v_mov_b32_dpp v204, v172 row_half_mirror row_mask:0xf bank_mask:0xf
	v_mov_b32_dpp v205, v173 row_half_mirror row_mask:0xf bank_mask:0xf
	v_mov_b32_dpp v206, v174 row_half_mirror row_mask:0xf bank_mask:0xf
	v_mov_b32_dpp v207, v175 row_half_mirror row_mask:0xf bank_mask:0xf
	v_mov_b32_dpp v208, v176 row_half_mirror row_mask:0xf bank_mask:0xf
	v_mov_b32_dpp v209, v177 row_half_mirror row_mask:0xf bank_mask:0xf
	v_mov_b32_dpp v210, v178 row_half_mirror row_mask:0xf bank_mask:0xf
	v_mov_b32_dpp v211, v179 row_half_mirror row_mask:0xf bank_mask:0xf
	v_mov_b32_dpp v212, v180 row_half_mirror row_mask:0xf bank_mask:0xf
	v_mov_b32_dpp v213, v181 row_half_mirror row_mask:0xf bank_mask:0xf
	v_mov_b32_dpp v214, v182 row_half_mirror row_mask:0xf bank_mask:0xf
	v_mov_b32_dpp v215, v183 row_half_mirror row_mask:0xf bank_mask:0xf
	v_mov_b32_dpp v216, v196 quad_perm:[3,2,1,0] row_mask:0xf bank_mask:0xf
	v_mov_b32_dpp v217, v197 quad_perm:[3,2,1,0] row_mask:0xf bank_mask:0xf
	v_mov_b32_dpp v218, v198 quad_perm:[3,2,1,0] row_mask:0xf bank_mask:0xf
	v_mov_b32_dpp v219, v199 quad_perm:[3,2,1,0] row_mask:0xf bank_mask:0xf
	v_mov_b32_dpp v220, v200 quad_perm:[3,2,1,0] row_mask:0xf bank_mask:0xf
	v_mov_b32_dpp v221, v201 quad_perm:[3,2,1,0] row_mask:0xf bank_mask:0xf
	v_mov_b32_dpp v222, v202 quad_perm:[3,2,1,0] row_mask:0xf bank_mask:0xf
	v_mov_b32_dpp v223, v203 quad_perm:[3,2,1,0] row_mask:0xf bank_mask:0xf
	v_mov_b32_dpp v224, v204 quad_perm:[3,2,1,0] row_mask:0xf bank_mask:0xf
	v_mov_b32_dpp v225, v205 quad_perm:[3,2,1,0] row_mask:0xf bank_mask:0xf
	v_mov_b32_dpp v226, v206 quad_perm:[3,2,1,0] row_mask:0xf bank_mask:0xf
	v_mov_b32_dpp v227, v207 quad_perm:[3,2,1,0] row_mask:0xf bank_mask:0xf
	v_mov_b32_dpp v228, v208 quad_perm:[3,2,1,0] row_mask:0xf bank_mask:0xf
	v_mov_b32_dpp v229, v209 quad_perm:[3,2,1,0] row_mask:0xf bank_mask:0xf
	v_mov_b32_dpp v230, v210 quad_perm:[3,2,1,0] row_mask:0xf bank_mask:0xf
	v_mov_b32_dpp v231, v211 quad_perm:[3,2,1,0] row_mask:0xf bank_mask:0xf
	v_mov_b32_dpp v232, v212 quad_perm:[3,2,1,0] row_mask:0xf bank_mask:0xf
	v_mov_b32_dpp v233, v213 quad_perm:[3,2,1,0] row_mask:0xf bank_mask:0xf
	v_mov_b32_dpp v234, v214 quad_perm:[3,2,1,0] row_mask:0xf bank_mask:0xf
	v_mov_b32_dpp v235, v215 quad_perm:[3,2,1,0] row_mask:0xf bank_mask:0xf
	v_mul_f32_e32 v216, v141, v216
	v_mul_f32_e32 v217, v143, v217
	v_mul_f32_e32 v218, v145, v218
	v_mul_f32_e32 v219, v147, v219
	v_mul_f32_e32 v220, v141, v220
	v_mul_f32_e32 v221, v143, v221
	v_mul_f32_e32 v222, v145, v222
	v_mul_f32_e32 v223, v147, v223
	v_mul_f32_e32 v224, v149, v224
	v_mul_f32_e32 v225, v151, v225
	v_mul_f32_e32 v226, v153, v226
	v_mul_f32_e32 v227, v155, v227
	v_mul_f32_e32 v228, v149, v228
	v_mul_f32_e32 v229, v151, v229
	v_mul_f32_e32 v230, v153, v230
	v_mul_f32_e32 v231, v155, v231
	v_mul_f32_e32 v232, v157, v232
	v_mul_f32_e32 v233, v159, v233
	v_mul_f32_e32 v234, v161, v234
	v_mul_f32_e32 v235, v163, v235
	v_fmac_f32_e32 v216, v140, v164
	v_fmac_f32_e32 v217, v142, v165
	v_fmac_f32_e32 v218, v144, v166
	v_fmac_f32_e32 v219, v146, v167
	v_fmac_f32_e32 v220, v140, v168
	v_fmac_f32_e32 v221, v142, v169
	v_fmac_f32_e32 v222, v144, v170
	v_fmac_f32_e32 v223, v146, v171
	v_fmac_f32_e32 v224, v148, v172
	v_fmac_f32_e32 v225, v150, v173
	v_fmac_f32_e32 v226, v152, v174
	v_fmac_f32_e32 v227, v154, v175
	v_fmac_f32_e32 v228, v148, v176
	v_fmac_f32_e32 v229, v150, v177
	v_fmac_f32_e32 v230, v152, v178
	v_fmac_f32_e32 v231, v154, v179
	v_fmac_f32_e32 v232, v156, v180
	v_fmac_f32_e32 v233, v158, v181
	v_fmac_f32_e32 v234, v160, v182
	v_fmac_f32_e32 v235, v162, v183
	v_mul_f32_e32 v216, 0x3e38aa3b, v216
	v_mul_f32_e32 v217, 0x3e38aa3b, v217
	v_mul_f32_e32 v218, 0x3e38aa3b, v218
	v_mul_f32_e32 v219, 0x3e38aa3b, v219
	v_mul_f32_e32 v220, 0x3e38aa3b, v220
	v_mul_f32_e32 v221, 0x3e38aa3b, v221
	v_mul_f32_e32 v222, 0x3e38aa3b, v222
	v_mul_f32_e32 v223, 0x3e38aa3b, v223
	v_mul_f32_e32 v224, 0x3e38aa3b, v224
	v_mul_f32_e32 v225, 0x3e38aa3b, v225
	v_mul_f32_e32 v226, 0x3e38aa3b, v226
	v_mul_f32_e32 v227, 0x3e38aa3b, v227
	v_mul_f32_e32 v228, 0x3e38aa3b, v228
	v_mul_f32_e32 v229, 0x3e38aa3b, v229
	v_mul_f32_e32 v230, 0x3e38aa3b, v230
	v_mul_f32_e32 v231, 0x3e38aa3b, v231
	v_cvt_pk_bf16_f32 v58, v216, v217
	v_cvt_pk_bf16_f32 v59, v218, v219
	v_cvt_pk_bf16_f32 v60, v220, v221
	v_cvt_pk_bf16_f32 v61, v222, v223
	v_cvt_pk_bf16_f32 v62, v224, v225
	v_cvt_pk_bf16_f32 v63, v226, v227
	v_cvt_pk_bf16_f32 v64, v228, v229
	v_cvt_pk_bf16_f32 v65, v230, v231
	v_cvt_pk_bf16_f32 v66, v232, v233
	v_cvt_pk_bf16_f32 v67, v234, v235
	global_store_dwordx2 v2, v[58:59], s[16:17]
	global_store_dwordx2 v2, v[60:61], s[16:17] offset:512
	global_store_dwordx2 v3, v[62:63], s[16:17]
	global_store_dwordx2 v3, v[64:65], s[16:17] offset:512
	global_store_dwordx2 v4, v[66:67], s[16:17] offset:1024
.Lprep_skip_L1_3:
	s_mul_i32 s20, s19, 4
	s_add_i32 s18, s18, s20
	s_cmp_lt_u32 s18, 0x2000
	s_cbranch_scc1 .Lprep_loop_L1
.Lprep_done_L1:
.LBB0_2731:
	s_getreg_b32 s8, hwreg(HW_REG_XCC_ID, 0, 4)
	s_waitcnt vmcnt(0)
	s_barrier
	s_and_saveexec_b64 s[0:1], s[46:47]
	s_cbranch_execz .LBB0_2783
	s_add_i32 s9, 0, 0x20160
	v_mov_b32_e32 v0, s9
	s_waitcnt vmcnt(0) expcnt(0) lgkmcnt(0)
	ds_read_b32 v2, v0
	s_add_i32 s9, 0, 0x20164
	v_mov_b32_e32 v0, s9
	ds_read_b32 v0, v0
	s_and_b32 s52, s8, 15
	s_waitcnt lgkmcnt(1)
	v_cmp_ne_u32_e32 vcc, 0, v2
	s_cbranch_vccnz .LBB0_2747
	s_add_u32 s8, s66, 0x1200
	s_addc_u32 s9, s67, 0
	s_add_u32 s10, s66, 0x1400
	s_addc_u32 s11, s67, 0
	s_add_u32 s12, s66, 0x1500
	s_addc_u32 s13, s67, 0
	s_add_u32 s14, s66, 0x1600
	s_addc_u32 s15, s67, 0
	s_add_u32 s16, s66, 0x1700
	s_addc_u32 s17, s67, 0
	s_add_u32 s18, s66, 0x1800
	s_addc_u32 s19, s67, 0
	s_add_u32 s20, s66, 0x1900
	s_addc_u32 s21, s67, 0
	s_add_u32 s22, s66, 0x1a00
	s_addc_u32 s23, s67, 0
	s_add_u32 s24, s66, 0x1b00
	s_addc_u32 s25, s67, 0
	s_add_u32 s26, s66, 0x1c00
	s_addc_u32 s27, s67, 0
	s_add_u32 s28, s66, 0x1d00
	s_addc_u32 s29, s67, 0
	s_add_u32 s30, s66, 0x1e00
	s_addc_u32 s31, s67, 0
	s_add_u32 s34, s66, 0x1f00
	s_addc_u32 s35, s67, 0
	s_add_u32 s36, s66, 0x2000
	s_addc_u32 s37, s67, 0
	s_add_u32 s38, s66, 0x2100
	s_addc_u32 s39, s67, 0
	s_add_u32 s40, s66, 0x2200
	s_addc_u32 s41, s67, 0
	s_mul_i32 s53, s65, s74
	s_add_u32 s42, s66, 0x2300
	s_mul_i32 s53, s53, s64
	s_addc_u32 s43, s67, 0
	s_mov_b32 s54, 1
	v_mov_b32_e32 v16, 0
	s_branch .LBB0_2735

	.amdhsa_kernel _Z10fwd_kernel4Args
		.amdhsa_group_segment_fixed_size 0
		.amdhsa_private_segment_fixed_size 0
		.amdhsa_kernarg_size 528
		.amdhsa_user_sgpr_count 2
		.amdhsa_user_sgpr_dispatch_ptr 0
		.amdhsa_user_sgpr_queue_ptr 0
		.amdhsa_user_sgpr_kernarg_segment_ptr 1
		.amdhsa_user_sgpr_dispatch_id 0
		.amdhsa_user_sgpr_kernarg_preload_length 0
		.amdhsa_user_sgpr_kernarg_preload_offset 0
		.amdhsa_user_sgpr_private_segment_size 0
		.amdhsa_uses_dynamic_stack 0
		.amdhsa_enable_private_segment 0
		.amdhsa_system_sgpr_workgroup_id_x 1
		.amdhsa_system_sgpr_workgroup_id_y 0
		.amdhsa_system_sgpr_workgroup_id_z 0
		.amdhsa_system_sgpr_workgroup_info 0
		.amdhsa_system_vgpr_workitem_id 2
		.amdhsa_next_free_vgpr 239
		.amdhsa_next_free_sgpr 98
		.amdhsa_accum_offset 240
		.amdhsa_reserve_vcc 1
		.amdhsa_float_round_mode_32 0
		.amdhsa_float_round_mode_16_64 0
		.amdhsa_float_denorm_mode_32 3
		.amdhsa_float_denorm_mode_16_64 3
		.amdhsa_dx10_clamp 1
		.amdhsa_ieee_mode 1
		.amdhsa_fp16_overflow 0
		.amdhsa_tg_split 0
		.amdhsa_exception_fp_ieee_invalid_op 0
		.amdhsa_exception_fp_denorm_src 0
		.amdhsa_exception_fp_ieee_div_zero 0
		.amdhsa_exception_fp_ieee_overflow 0
		.amdhsa_exception_fp_ieee_underflow 0
		.amdhsa_exception_fp_ieee_inexact 0
		.amdhsa_exception_int_div_zero 0
	.end_amdhsa_kernel

.Lfunc_end0:
	.size	_Z10fwd_kernel4Args, .Lfunc_end0-_Z10fwd_kernel4Args
	.set _Z10fwd_kernel4Args.num_vgpr, 239
	.set _Z10fwd_kernel4Args.num_agpr, 0
	.set _Z10fwd_kernel4Args.numbered_sgpr, 98
	.set _Z10fwd_kernel4Args.num_named_barrier, 0
	.set _Z10fwd_kernel4Args.private_seg_size, 0
	.set _Z10fwd_kernel4Args.uses_vcc, 1
	.set _Z10fwd_kernel4Args.uses_flat_scratch, 0
	.set _Z10fwd_kernel4Args.has_dyn_sized_stack, 0
	.set _Z10fwd_kernel4Args.has_recursion, 0
	.set _Z10fwd_kernel4Args.has_indirect_call, 0

amdhsa.kernels:
  - .agpr_count:     0
    .args:
      - .offset:         0
        .size:           272
        .value_kind:     by_value
      - .offset:         272
        .size:           4
        .value_kind:     hidden_block_count_x
      - .offset:         276
        .size:           4
        .value_kind:     hidden_block_count_y
      - .offset:         280
        .size:           4
        .value_kind:     hidden_block_count_z
      - .offset:         284
        .size:           2
        .value_kind:     hidden_group_size_x
      - .offset:         286
        .size:           2
        .value_kind:     hidden_group_size_y
      - .offset:         288
        .size:           2
        .value_kind:     hidden_group_size_z
      - .offset:         290
        .size:           2
        .value_kind:     hidden_remainder_x
      - .offset:         292
        .size:           2
        .value_kind:     hidden_remainder_y
      - .offset:         294
        .size:           2
        .value_kind:     hidden_remainder_z
      - .offset:         312
        .size:           8
        .value_kind:     hidden_global_offset_x
      - .offset:         320
        .size:           8
        .value_kind:     hidden_global_offset_y
      - .offset:         328
        .size:           8
        .value_kind:     hidden_global_offset_z
      - .offset:         336
        .size:           2
        .value_kind:     hidden_grid_dims
      - .offset:         360
        .size:           8
        .value_kind:     hidden_multigrid_sync_arg
      - .offset:         392
        .size:           4
        .value_kind:     hidden_dynamic_lds_size
    .group_segment_fixed_size: 0
    .kernarg_segment_align: 8
    .kernarg_segment_size: 528
    .language:       OpenCL C
    .language_version:
      - 2
      - 0
    .max_flat_workgroup_size: 512
    .name:           _Z10fwd_kernel4Args
    .private_segment_fixed_size: 0
    .sgpr_count:     104
    .sgpr_spill_count: 0
    .symbol:         _Z10fwd_kernel4Args.kd
    .uniform_work_group_size: 1
    .uses_dynamic_stack: false
    .vgpr_count:     239
    .vgpr_spill_count: 0
    .wavefront_size: 64
